# retention phase rewritten by hand: 32-key subtiles, K/V via LDS-DMA 3-slot rings, wave-private swizzled V, one barrier per subtile, epilogue loads in flight
# speedup vs baseline: 1.0610x; 1.0521x over previous
; __device__ __forceinline__ void ret_unit(ldsp lds, bf16_t* R, const bf16_t* RC, int b, int h, int qblk, float lgf2, float lgb2, const int tid_in) {
;     int tl0_ = tid_in; asm volatile("" : "+v"(tl0_));
;     const int tid_outer = tl0_;
;     const int wid = __builtin_amdgcn_readfirstlane(tid_outer >> 6);
;     const ldsp Ks = lds, Vs = lds + 67584, Ps = lds + 134144;
;     const int q0 = qblk * 64, rowq0 = b * SEQ + q0;
;     const int qb = wid & 3, kbp = wid >> 2;
;     bf16x8 qf[8];
;     { const int l15 = tid_outer & 15, lg = (tid_outer & 63) >> 4;
; #pragma unroll
;       for (int ks = 0; ks < 8; ++ks) qf[ks] = *(const bf16x8*)(R + (size_t)(rowq0 + 16 * qb + l15) * 6144 + h * 256 + 32 * ks + 8 * lg); }
;     u32x4 vr[8];
; __device__ __forceinline__ void ret_phase(ldsp lds, bf16_t* R, const bf16_t* RC, const float* decay, const int tid, const int bx) {
;     const int xcd = bx & 7, slot = bx >> 3;
;     for (int i = 0; i < 4; ++i) {
;         const int bh = 8 * i + xcd, b = bh >> 2, h = bh & 3;
;         const float lgf2 = decay[h], lgb2 = decay[4 + h];
;         ret_unit(lds, R, RC, b, h, slot, lgf2, lgb2, tid);
.LBB0_590:
	s_and_b64 vcc, exec, s[8:9]
	s_cbranch_vccz .LBB0_810
	s_cmp_lt_i32 s47, 2
	s_mov_b64 s[4:5], -1
	s_cbranch_scc1 .LBB0_746
	s_cmp_eq_u32 s47, 2
	s_movk_i32 s4, 0x3000
	s_cbranch_scc0 .LBB0_745
	s_waitcnt lgkmcnt(0)
	s_load_dwordx2 s[0:1], s[62:63], 0xc0
	v_and_b32_e32 v211, 63, v196
	v_and_b32_e32 v209, 15, v196
	v_bfe_u32 v210, v196, 4, 2
	v_lshrrev_b32_e32 v212, 6, v196
	s_and_b32 s7, s96, 3
	s_lshr_b32 s9, s96, 3
	s_lshl_b32 s13, s9, 6
	v_readfirstlane_b32 s10, v212
	s_lshr_b32 s14, s10, 2
	s_and_b32 s41, s10, 3
	s_waitcnt lgkmcnt(0)
	s_lshl_b32 s46, s7, 2
	s_add_u32 s4, s0, 0xd8000
	s_addc_u32 s5, s1, 0
	s_add_u32 s4, s4, s46
	s_addc_u32 s5, s5, 0
	global_load_dword v207, v97, s[4:5]
	global_load_dword v208, v97, s[4:5] offset:16
	s_mul_i32 s54, s10, 2112
	s_mul_i32 s55, s10, 12288
	s_add_i32 s55, s55, 50688
	v_lshrrev_b32_e32 v212, 5, v211
	v_and_b32_e32 v213, 31, v211
	v_xor_b32_e32 v213, v213, v212
	v_lshlrev_b32_e32 v213, 4, v213
	s_lshl_b32 s46, s14, 4
	s_lshl_b32 s48, s41, 1
	s_add_i32 s46, s46, s48
	v_lshl_add_u32 v214, v212, 3, s46
	s_movk_i32 s48, 0x3000
	v_mad_u32_u24 v189, v214, s48, v213
	v_add_u32_e32 v190, 0x3000, v189
	s_movk_i32 s48, 0x1800
	v_mad_u32_u24 v191, v214, s48, v213
	v_add_u32_e32 v192, 0x1800, v191
	v_lshrrev_b32_e32 v212, 3, v211
	v_and_b32_e32 v213, 7, v211
	v_bfe_u32 v214, v211, 4, 1
	v_lshlrev_b32_e32 v214, 1, v214
	v_xor_b32_e32 v213, v213, v214
	v_xor_b32_e32 v214, 4, v213
	v_lshlrev_b32_e32 v213, 4, v213
	v_lshlrev_b32_e32 v214, 4, v214
	s_lshl_b32 s46, s10, 7
	s_lshl_b32 s48, s7, 9
	s_add_i32 s46, s46, s48
	s_addk_i32 s46, 0x800
	s_movk_i32 s48, 0x3000
	v_mov_b32_e32 v215, s46
	v_mad_u32_u24 v215, v212, s48, v215
	v_add_u32_e32 v193, v215, v213
	v_add_u32_e32 v194, v215, v214
	v_add_u32_e32 v194, 0x18000, v194
	v_add_u32_e32 v195, v215, v213
	v_add_u32_e32 v195, 0x30000, v195
	v_add_u32_e32 v197, v215, v214
	v_add_u32_e32 v197, 0x48000, v197
	s_movk_i32 s48, 0x1800
	v_mov_b32_e32 v215, s46
	v_mad_u32_u24 v215, v212, s48, v215
	v_add_u32_e32 v198, v215, v213
	v_add_u32_e32 v199, v215, v214
	v_add_u32_e32 v199, 0xc000, v199
	v_add_u32_e32 v200, v215, v213
	v_add_u32_e32 v200, 0x18000, v200
	v_add_u32_e32 v202, v215, v214
	v_add_u32_e32 v202, 0x24000, v202
	s_lshl_b32 s46, s41, 4
	s_add_i32 s46, s46, s13
	s_lshl_b32 s48, s14, 4
	s_sub_i32 s46, s46, s48
	v_lshlrev_b32_e32 v212, 2, v210
	v_sub_u32_e32 v212, v209, v212
	v_add_u32_e32 v203, s46, v212
	v_add_u32_e32 v204, -1, v203
	v_add_u32_e32 v205, -2, v203
	v_add_u32_e32 v206, -3, v203
	v_lshrrev_b32_e32 v212, 3, v209
	v_and_b32_e32 v213, 7, v209
	s_lshl_b32 s46, s14, 3
	v_add_u32_e32 v213, s46, v213
	s_movk_i32 s48, 0x420
	v_lshlrev_b32_e32 v214, 9, v212
	v_mad_u32_u24 v182, v213, s48, v214
	v_xor_b32_e32 v214, v210, v212
	v_lshl_add_u32 v182, v214, 4, v182
	v_lshlrev_b32_e32 v213, 10, v210
	v_lshrrev_b32_e32 v214, 2, v209
	v_lshl_add_u32 v213, v214, 7, v213
	v_bfe_u32 v214, v209, 1, 1
	v_lshl_add_u32 v213, v214, 4, v213
	v_and_b32_e32 v214, 1, v209
	v_lshl_add_u32 v213, v214, 3, v213
	v_add_u32_e32 v213, s55, v213
	v_and_b32_e32 v214, 1, v210
	v_lshl_or_b32 v214, v214, 1, v212
	v_xor_b32_e32 v215, 0, v214
	v_lshl_add_u32 v183, v215, 5, v213
	v_xor_b32_e32 v215, 1, v214
	v_lshl_add_u32 v184, v215, 5, v213
	v_xor_b32_e32 v215, 2, v214
	v_lshl_add_u32 v185, v215, 5, v213
	v_xor_b32_e32 v215, 3, v214
	v_lshl_add_u32 v186, v215, 5, v213
	v_mul_u32_u24_e32 v212, 0x50, v209
	v_lshl_add_u32 v187, v210, 4, v212
	v_add_u32_e32 v187, 0x24600, v187
	s_mul_i32 s46, s41, 1280
	s_lshl_b32 s48, s14, 5
	s_add_i32 s46, s46, s48
	s_add_i32 s46, s46, 0x24600
	v_lshl_add_u32 v188, v210, 3, v212
	v_add_u32_e32 v188, s46, v188
	s_lshl_b32 s46, s41, 4
	v_add_u32_e32 v212, s46, v209
	v_mul_u32_u24_e32 v212, 0x3000, v212
	v_lshl_add_u32 v219, v210, 4, v212
	v_mul_u32_u24_e32 v212, 0x3000, v209
	s_lshl_b32 s46, s10, 7
	v_lshl_add_u32 v212, v210, 3, v212
	v_add_u32_e32 v226, s46, v212
	v_add_u32_e32 v227, 0x30000, v226
	v_add_u32_e32 v228, 0x60000, v226
	v_add_u32_e32 v229, 0x90000, v226
	s_waitcnt vmcnt(0)
	v_readfirstlane_b32 s11, v207
	v_readfirstlane_b32 s12, v208
	s_mov_b32 s3, 0
.Lret_unit:
	s_bfe_u32 s8, s96, 0x10002
	s_lshl_b32 s41, s3, 1
	s_or_b32 s8, s8, s41
	s_mul_i32 s41, s8, 0x1800000
	s_add_u32 s22, s0, 0x9400000
	s_addc_u32 s23, s1, 0
	s_add_u32 s22, s22, s41
	s_addc_u32 s23, s23, 0
	s_mul_i32 s41, s8, 0x180000
	s_add_u32 s24, s0, 0x15400000
	s_addc_u32 s25, s1, 0
	s_add_u32 s24, s24, s41
	s_addc_u32 s25, s25, 0
	s_lshl_b32 s46, s7, 9
	s_add_u32 s78, s22, s46
	s_addc_u32 s79, s23, 0
	s_add_u32 s78, s78, 0x800
	s_addc_u32 s79, s79, 0
	s_add_u32 s80, s24, s46
	s_addc_u32 s81, s25, 0
	s_mul_i32 s41, s13, 0x3000
	s_add_u32 s86, s22, s41
	s_addc_u32 s87, s23, 0
	s_add_u32 s86, s86, s46
	s_addc_u32 s87, s87, 0
	s_barrier
	global_load_dwordx4 v[64:67], v219, s[86:87] offset:0
	global_load_dwordx4 v[68:71], v219, s[86:87] offset:64
	global_load_dwordx4 v[72:75], v219, s[86:87] offset:128
	global_load_dwordx4 v[76:79], v219, s[86:87] offset:192
	global_load_dwordx4 v[80:83], v219, s[86:87] offset:256
	global_load_dwordx4 v[84:87], v219, s[86:87] offset:320
	global_load_dwordx4 v[88:91], v219, s[86:87] offset:384
	global_load_dwordx4 v[92:95], v219, s[86:87] offset:448
	s_mov_b32 s29, s9
	s_mov_b32 s34, s9
	s_mov_b32 s37, s9
	s_mov_b32 s31, 0
	s_mov_b32 s36, 0
	s_mov_b32 s38, 0
	s_cmp_lt_u32 s29, 32
	s_cbranch_scc0 .Lret_dctx_1
	s_mul_i32 s41, s29, 0xc0000
	s_mul_i32 s46, s31, 0x60000
	s_add_u32 s42, s78, s41
	s_addc_u32 s43, s79, 0
	s_add_u32 s42, s42, s46
	s_addc_u32 s43, s43, 0
	s_add_i32 m0, s54, 0
	s_nop 0
	global_load_lds_dwordx4 v189, s[42:43]
	s_add_i32 m0, s54, 1056
	s_nop 0
	global_load_lds_dwordx4 v190, s[42:43]
	s_branch .Lret_ddone_2
.Lret_dctx_1:
	s_sub_i32 s41, s29, 32
	s_mul_i32 s41, s41, 0x60000
	s_mul_i32 s46, s31, 0x30000
	s_add_u32 s42, s80, s41
	s_addc_u32 s43, s81, 0
	s_add_u32 s42, s42, s46
	s_addc_u32 s43, s43, 0
	s_add_i32 m0, s54, 0
	s_nop 0
	global_load_lds_dwordx4 v191, s[42:43]
	s_add_i32 m0, s54, 1056
	s_nop 0
	global_load_lds_dwordx4 v192, s[42:43]
.Lret_ddone_2:
	s_xor_b32 s31, s31, 1
	s_cmp_eq_u32 s31, 0
	s_cselect_b32 s41, 1, 0
	s_add_i32 s29, s29, s41
	s_cmp_eq_u32 s29, 36
	s_cselect_b32 s29, 0, s29
	s_cmp_lt_u32 s29, 32
	s_cbranch_scc0 .Lret_dctx_3
	s_mul_i32 s41, s29, 0xc0000
	s_mul_i32 s46, s31, 0x60000
	s_add_u32 s42, s78, s41
	s_addc_u32 s43, s79, 0
	s_add_u32 s42, s42, s46
	s_addc_u32 s43, s43, 0
	s_add_i32 m0, s54, 16896
	s_nop 0
	global_load_lds_dwordx4 v189, s[42:43]
	s_add_i32 m0, s54, 17952
	s_nop 0
	global_load_lds_dwordx4 v190, s[42:43]
	s_branch .Lret_ddone_4
.Lret_dctx_3:
	s_sub_i32 s41, s29, 32
	s_mul_i32 s41, s41, 0x60000
	s_mul_i32 s46, s31, 0x30000
	s_add_u32 s42, s80, s41
	s_addc_u32 s43, s81, 0
	s_add_u32 s42, s42, s46
	s_addc_u32 s43, s43, 0
	s_add_i32 m0, s54, 16896
	s_nop 0
	global_load_lds_dwordx4 v191, s[42:43]
	s_add_i32 m0, s54, 17952
	s_nop 0
	global_load_lds_dwordx4 v192, s[42:43]
.Lret_ddone_4:
	s_xor_b32 s31, s31, 1
	s_cmp_eq_u32 s31, 0
	s_cselect_b32 s41, 1, 0
	s_add_i32 s29, s29, s41
	s_cmp_eq_u32 s29, 36
	s_cselect_b32 s29, 0, s29
	s_cmp_lt_u32 s29, 32
	s_cbranch_scc0 .Lret_dctx_5
	s_mul_i32 s41, s29, 0xc0000
	s_mul_i32 s46, s31, 0x60000
	s_add_u32 s42, s78, s41
	s_addc_u32 s43, s79, 0
	s_add_u32 s42, s42, s46
	s_addc_u32 s43, s43, 0
	s_add_i32 m0, s54, 33792
	s_nop 0
	global_load_lds_dwordx4 v189, s[42:43]
	s_add_i32 m0, s54, 34848
	s_nop 0
	global_load_lds_dwordx4 v190, s[42:43]
	s_branch .Lret_ddone_6
.Lret_dctx_5:
	s_sub_i32 s41, s29, 32
	s_mul_i32 s41, s41, 0x60000
	s_mul_i32 s46, s31, 0x30000
	s_add_u32 s42, s80, s41
	s_addc_u32 s43, s81, 0
	s_add_u32 s42, s42, s46
	s_addc_u32 s43, s43, 0
	s_add_i32 m0, s54, 33792
	s_nop 0
	global_load_lds_dwordx4 v191, s[42:43]
	s_add_i32 m0, s54, 34848
	s_nop 0
	global_load_lds_dwordx4 v192, s[42:43]
.Lret_ddone_6:
	s_xor_b32 s31, s31, 1
	s_cmp_eq_u32 s31, 0
	s_cselect_b32 s41, 1, 0
	s_add_i32 s29, s29, s41
	s_cmp_eq_u32 s29, 36
	s_cselect_b32 s29, 0, s29
	s_cmp_lt_u32 s34, 32
	s_cbranch_scc0 .Lret_dctx_7
	s_mul_i32 s41, s34, 0xc0000
	s_mul_i32 s46, s36, 0x60000
	s_add_u32 s44, s78, s41
	s_addc_u32 s45, s79, 0
	s_add_u32 s44, s44, s46
	s_addc_u32 s45, s45, 0
	s_add_i32 m0, s55, 0
	s_nop 0
	global_load_lds_dwordx4 v193, s[44:45]
	s_add_i32 m0, s55, 1024
	s_nop 0
	global_load_lds_dwordx4 v194, s[44:45]
	s_add_i32 m0, s55, 2048
	s_nop 0
	global_load_lds_dwordx4 v195, s[44:45]
	s_add_i32 m0, s55, 3072
	s_nop 0
	global_load_lds_dwordx4 v197, s[44:45]
	s_branch .Lret_ddone_8
.Lret_dctx_7:
	s_sub_i32 s41, s34, 32
	s_mul_i32 s41, s41, 0x60000
	s_mul_i32 s46, s36, 0x30000
	s_add_u32 s44, s80, s41
	s_addc_u32 s45, s81, 0
	s_add_u32 s44, s44, s46
	s_addc_u32 s45, s45, 0
	s_add_i32 m0, s55, 0
	s_nop 0
	global_load_lds_dwordx4 v198, s[44:45]
	s_add_i32 m0, s55, 1024
	s_nop 0
	global_load_lds_dwordx4 v199, s[44:45]
	s_add_i32 m0, s55, 2048
	s_nop 0
	global_load_lds_dwordx4 v200, s[44:45]
	s_add_i32 m0, s55, 3072
	s_nop 0
	global_load_lds_dwordx4 v202, s[44:45]
.Lret_ddone_8:
	s_xor_b32 s36, s36, 1
	s_cmp_eq_u32 s36, 0
	s_cselect_b32 s41, 1, 0
	s_add_i32 s34, s34, s41
	s_cmp_eq_u32 s34, 36
	s_cselect_b32 s34, 0, s34
	s_cmp_lt_u32 s34, 32
	s_cbranch_scc0 .Lret_dctx_9
	s_mul_i32 s41, s34, 0xc0000
	s_mul_i32 s46, s36, 0x60000
	s_add_u32 s44, s78, s41
	s_addc_u32 s45, s79, 0
	s_add_u32 s44, s44, s46
	s_addc_u32 s45, s45, 0
	s_add_i32 m0, s55, 4096
	s_nop 0
	global_load_lds_dwordx4 v193, s[44:45]
	s_add_i32 m0, s55, 5120
	s_nop 0
	global_load_lds_dwordx4 v194, s[44:45]
	s_add_i32 m0, s55, 6144
	s_nop 0
	global_load_lds_dwordx4 v195, s[44:45]
	s_add_i32 m0, s55, 7168
	s_nop 0
	global_load_lds_dwordx4 v197, s[44:45]
	s_branch .Lret_ddone_10
.Lret_dctx_9:
	s_sub_i32 s41, s34, 32
	s_mul_i32 s41, s41, 0x60000
	s_mul_i32 s46, s36, 0x30000
	s_add_u32 s44, s80, s41
	s_addc_u32 s45, s81, 0
	s_add_u32 s44, s44, s46
	s_addc_u32 s45, s45, 0
	s_add_i32 m0, s55, 4096
	s_nop 0
	global_load_lds_dwordx4 v198, s[44:45]
	s_add_i32 m0, s55, 5120
	s_nop 0
	global_load_lds_dwordx4 v199, s[44:45]
	s_add_i32 m0, s55, 6144
	s_nop 0
	global_load_lds_dwordx4 v200, s[44:45]
	s_add_i32 m0, s55, 7168
	s_nop 0
	global_load_lds_dwordx4 v202, s[44:45]
; #define RET_BAR() do { asm volatile("s_waitcnt lgkmcnt(0)" ::: "memory"); __builtin_amdgcn_s_barrier(); asm volatile("" ::: "memory"); } while (0)
; #define RET_LOADV(t) do { RET_KV(t) const char* vb_ = kb_ + (1024 + h * 256) * 2; const unsigned lo_ = (unsigned)(tid >> 6) * kp_ + (unsigned)(tid & 63) * 16u; \
;         _Pragma("unroll") for (int i_ = 0; i_ < 8; ++i_) vr[i_] = *(const u32x4*)(vb_ + (size_t)(8u * i_) * kp_ + lo_); } while (0)
; #define RET_STOREV() do { _Pragma("unroll") for (int i_ = 0; i_ < 8; ++i_) *(LAS u32x4*)(Vs + ((tid >> 6) + 8 * i_) * 1040 + (tid & 63) * 16) = vr[i_]; } while (0)
; __device__ __forceinline__ void ret_unit(ldsp lds, bf16_t* R, const bf16_t* RC, int b, int h, int qblk, float lgf2, float lgb2, const int tid_in) {
;     ...
;     f32x4 o[4][4];
; #pragma unroll
;     for (int db = 0; db < 4; ++db)
; #pragma unroll
;         for (int q4 = 0; q4 < 4; ++q4) o[db][q4] = (f32x4){0.f, 0.f, 0.f, 0.f};
;     ...
;     { const int tid = tid_outer, lane = tid & 63, l15 = lane & 15, lg = lane >> 4;
;       RET_BAR();
;       RET_DMAK(TI(0), 0); RET_DMAK(TI(1), 1); RET_LOADV(TI(0));
;       asm volatile("s_waitcnt vmcnt(0)" ::: "memory");
;       RET_STOREV();
;       RET_BAR();
;       RET_S(0, TI(0));
;       RET_LOADV(TI(1));
;       RET_BAR();
;       RET_DMAK(TI(2), 0); }
.Lret_ddone_10:
	s_xor_b32 s36, s36, 1
	s_cmp_eq_u32 s36, 0
	s_cselect_b32 s41, 1, 0
	s_add_i32 s34, s34, s41
	s_cmp_eq_u32 s34, 36
	s_cselect_b32 s34, 0, s34
	v_mov_b64_e32 v[0:1], 0
	v_mov_b64_e32 v[2:3], 0
	v_mov_b64_e32 v[4:5], 0
	v_mov_b64_e32 v[6:7], 0
	v_mov_b64_e32 v[8:9], 0
	v_mov_b64_e32 v[10:11], 0
	v_mov_b64_e32 v[12:13], 0
	v_mov_b64_e32 v[14:15], 0
	v_mov_b64_e32 v[16:17], 0
	v_mov_b64_e32 v[18:19], 0
	v_mov_b64_e32 v[20:21], 0
	v_mov_b64_e32 v[22:23], 0
	v_mov_b64_e32 v[24:25], 0
	v_mov_b64_e32 v[26:27], 0
	v_mov_b64_e32 v[28:29], 0
	v_mov_b64_e32 v[30:31], 0
	v_mov_b64_e32 v[32:33], 0
	v_mov_b64_e32 v[34:35], 0
	v_mov_b64_e32 v[36:37], 0
	v_mov_b64_e32 v[38:39], 0
	v_mov_b64_e32 v[40:41], 0
	v_mov_b64_e32 v[42:43], 0
	v_mov_b64_e32 v[44:45], 0
	v_mov_b64_e32 v[46:47], 0
	v_mov_b64_e32 v[48:49], 0
	v_mov_b64_e32 v[50:51], 0
	v_mov_b64_e32 v[52:53], 0
	v_mov_b64_e32 v[54:55], 0
	v_mov_b64_e32 v[56:57], 0
	v_mov_b64_e32 v[58:59], 0
	v_mov_b64_e32 v[60:61], 0
	v_mov_b64_e32 v[62:63], 0
	s_waitcnt vmcnt(12)
	s_barrier
	ds_read_b128 v[102:105], v182 offset:0
	ds_read_b128 v[106:109], v182 offset:64
	ds_read_b128 v[110:113], v182 offset:128
	ds_read_b128 v[114:117], v182 offset:192
	ds_read_b128 v[118:121], v182 offset:256
	ds_read_b128 v[122:125], v182 offset:320
	ds_read_b128 v[126:129], v182 offset:384
	ds_read_b128 v[130:133], v182 offset:448
	s_cmp_lt_u32 s37, 32
	s_cbranch_scc0 .Lret_wctx_11
	s_lshl_b32 s100, s37, 6
	s_lshl_b32 s41, s38, 5
	s_add_i32 s100, s100, s41
	v_subrev_u32_e32 v170, s100, v203
	v_subrev_u32_e32 v171, s100, v204
	v_subrev_u32_e32 v172, s100, v205
	v_subrev_u32_e32 v173, s100, v206
	v_cvt_f32_i32_e32 v174, v170
	v_cvt_f32_i32_e32 v175, v171
	v_cvt_f32_i32_e32 v176, v172
	v_cvt_f32_i32_e32 v177, v173
	v_cmp_gt_i32_e32 vcc, 0, v170
	s_nop 1
	v_cndmask_b32_e32 v178, v207, v208, vcc
	v_cmp_gt_i32_e32 vcc, 0, v171
	s_nop 1
	v_cndmask_b32_e32 v179, v207, v208, vcc
	v_cmp_gt_i32_e32 vcc, 0, v172
	s_nop 1
	v_cndmask_b32_e32 v180, v207, v208, vcc
	v_cmp_gt_i32_e32 vcc, 0, v173
	s_nop 1
	v_cndmask_b32_e32 v181, v207, v208, vcc
	v_mul_f32_e64 v178, v178, |v174|
	v_mul_f32_e64 v179, v179, |v175|
	v_mul_f32_e64 v180, v180, |v176|
	v_mul_f32_e64 v181, v181, |v177|
	v_exp_f32_e32 v166, v178
	v_exp_f32_e32 v167, v179
	v_exp_f32_e32 v168, v180
	v_exp_f32_e32 v169, v181
	s_branch .Lret_wdone_12
.Lret_wctx_11:
	s_sub_i32 s100, s37, 32
	s_lshl_b32 s100, s100, 6
	s_lshl_b32 s41, s38, 5
	s_add_i32 s100, s100, s41
	s_add_i32 s101, s100, 0x800
	s_sub_i32 s100, s100, 0x100
	v_subrev_u32_e32 v170, s100, v203
	v_sub_u32_e32 v174, s101, v203
	v_subrev_u32_e32 v171, s100, v204
	v_sub_u32_e32 v175, s101, v204
	v_subrev_u32_e32 v172, s100, v205
	v_sub_u32_e32 v176, s101, v205
	v_subrev_u32_e32 v173, s100, v206
	v_sub_u32_e32 v177, s101, v206
	v_cvt_f32_i32_e32 v170, v170
	v_cvt_f32_i32_e32 v174, v174
	v_cvt_f32_i32_e32 v171, v171
	v_cvt_f32_i32_e32 v175, v175
	v_cvt_f32_i32_e32 v172, v172
	v_cvt_f32_i32_e32 v176, v176
	v_cvt_f32_i32_e32 v173, v173
	v_cvt_f32_i32_e32 v177, v177
	v_mul_f32_e32 v170, s11, v170
	v_mul_f32_e32 v174, s12, v174
	v_mul_f32_e32 v171, s11, v171
	v_mul_f32_e32 v175, s12, v175
	v_mul_f32_e32 v172, s11, v172
	v_mul_f32_e32 v176, s12, v176
	v_mul_f32_e32 v173, s11, v173
	v_mul_f32_e32 v177, s12, v177
	v_exp_f32_e32 v170, v170
	v_exp_f32_e32 v174, v174
	v_exp_f32_e32 v171, v171
	v_exp_f32_e32 v175, v175
	v_exp_f32_e32 v172, v172
	v_exp_f32_e32 v176, v176
	v_exp_f32_e32 v173, v173
	v_exp_f32_e32 v177, v177
	s_nop 0
	v_add_f32_e32 v166, v170, v174
	v_add_f32_e32 v167, v171, v175
	v_add_f32_e32 v168, v172, v176
	v_add_f32_e32 v169, v173, v177
.Lret_wdone_12:
	s_xor_b32 s38, s38, 1
	s_cmp_eq_u32 s38, 0
	s_cselect_b32 s41, 1, 0
	s_add_i32 s37, s37, s41
	s_cmp_eq_u32 s37, 36
	s_cselect_b32 s37, 0, s37
	s_waitcnt lgkmcnt(7)
	v_mfma_f32_16x16x32_bf16 v[98:101], v[102:105], v[64:67], 0
	s_waitcnt lgkmcnt(6)
	v_mfma_f32_16x16x32_bf16 v[98:101], v[106:109], v[68:71], v[98:101]
	s_waitcnt lgkmcnt(5)
	v_mfma_f32_16x16x32_bf16 v[98:101], v[110:113], v[72:75], v[98:101]
	s_waitcnt lgkmcnt(4)
	v_mfma_f32_16x16x32_bf16 v[98:101], v[114:117], v[76:79], v[98:101]
	s_waitcnt lgkmcnt(3)
	v_mfma_f32_16x16x32_bf16 v[98:101], v[118:121], v[80:83], v[98:101]
	s_waitcnt lgkmcnt(2)
	v_mfma_f32_16x16x32_bf16 v[98:101], v[122:125], v[84:87], v[98:101]
	s_waitcnt lgkmcnt(1)
	v_mfma_f32_16x16x32_bf16 v[98:101], v[126:129], v[88:91], v[98:101]
	s_waitcnt lgkmcnt(0)
	v_mfma_f32_16x16x32_bf16 v[98:101], v[130:133], v[92:95], v[98:101]
	s_nop 7
	s_nop 1
	v_mul_f32_e32 v170, v98, v166
	v_mul_f32_e32 v171, v99, v167
	v_mul_f32_e32 v172, v100, v168
	v_mul_f32_e32 v173, v101, v169
	v_cvt_pk_bf16_f32 v174, v170, v171
	v_cvt_pk_bf16_f32 v175, v172, v173
	ds_write_b64 v188, v[174:175] offset:0
	s_waitcnt vmcnt(4)
	ds_read_b64_tr_b16 v[150:151], v183 offset:0
	ds_read_b64_tr_b16 v[152:153], v183 offset:512
	ds_read_b64_tr_b16 v[154:155], v184 offset:0
	ds_read_b64_tr_b16 v[156:157], v184 offset:512
	ds_read_b64_tr_b16 v[158:159], v185 offset:0
	ds_read_b64_tr_b16 v[160:161], v185 offset:512
	ds_read_b64_tr_b16 v[162:163], v186 offset:0
	ds_read_b64_tr_b16 v[164:165], v186 offset:512
	s_waitcnt lgkmcnt(8)
	s_barrier
	s_mov_b32 s27, 0
.Lret_loop:
	s_cmp_lt_u32 s29, 32
	s_cbranch_scc0 .Lret_dctx_13
	s_mul_i32 s41, s29, 0xc0000
	s_mul_i32 s46, s31, 0x60000
	s_add_u32 s42, s78, s41
	s_addc_u32 s43, s79, 0
	s_add_u32 s42, s42, s46
	s_addc_u32 s43, s43, 0
	s_add_i32 m0, s54, 0
	s_nop 0
	global_load_lds_dwordx4 v189, s[42:43]
	s_add_i32 m0, s54, 1056
	s_nop 0
	global_load_lds_dwordx4 v190, s[42:43]
	s_branch .Lret_ddone_14

.Lret_ddone_14:
	s_xor_b32 s31, s31, 1
	s_cmp_eq_u32 s31, 0
	s_cselect_b32 s41, 1, 0
	s_add_i32 s29, s29, s41
	s_cmp_eq_u32 s29, 36
	s_cselect_b32 s29, 0, s29
	s_cmp_lt_u32 s34, 32
	s_cbranch_scc0 .Lret_dctx_15
	s_mul_i32 s41, s34, 0xc0000
	s_mul_i32 s46, s36, 0x60000
	s_add_u32 s44, s78, s41
	s_addc_u32 s45, s79, 0
	s_add_u32 s44, s44, s46
	s_addc_u32 s45, s45, 0
	s_add_i32 m0, s55, 8192
	s_nop 0
	global_load_lds_dwordx4 v193, s[44:45]
	s_add_i32 m0, s55, 9216
	s_nop 0
	global_load_lds_dwordx4 v194, s[44:45]
	s_add_i32 m0, s55, 10240
	s_nop 0
	global_load_lds_dwordx4 v195, s[44:45]
	s_add_i32 m0, s55, 11264
	s_nop 0
	global_load_lds_dwordx4 v197, s[44:45]
	s_branch .Lret_ddone_16
.Lret_dctx_15:
	s_sub_i32 s41, s34, 32
	s_mul_i32 s41, s41, 0x60000
	s_mul_i32 s46, s36, 0x30000
	s_add_u32 s44, s80, s41
	s_addc_u32 s45, s81, 0
	s_add_u32 s44, s44, s46
	s_addc_u32 s45, s45, 0
	s_add_i32 m0, s55, 8192
	s_nop 0
	global_load_lds_dwordx4 v198, s[44:45]
	s_add_i32 m0, s55, 9216
	s_nop 0
	global_load_lds_dwordx4 v199, s[44:45]
	s_add_i32 m0, s55, 10240
	s_nop 0
	global_load_lds_dwordx4 v200, s[44:45]
	s_add_i32 m0, s55, 11264
	s_nop 0
	global_load_lds_dwordx4 v202, s[44:45]
.Lret_ddone_16:
	s_xor_b32 s36, s36, 1
	s_cmp_eq_u32 s36, 0
	s_cselect_b32 s41, 1, 0
	s_add_i32 s34, s34, s41
	s_cmp_eq_u32 s34, 36
	s_cselect_b32 s34, 0, s34
	ds_read_b128 v[102:105], v182 offset:16896
	ds_read_b128 v[106:109], v182 offset:16960
	ds_read_b128 v[110:113], v182 offset:17024
	ds_read_b128 v[114:117], v182 offset:17088
	ds_read_b128 v[118:121], v182 offset:17152
	ds_read_b128 v[122:125], v182 offset:17216
	ds_read_b128 v[126:129], v182 offset:17280
	ds_read_b128 v[130:133], v182 offset:17344
	ds_read_b128 v[134:137], v187 offset:0
	ds_read_b128 v[138:141], v187 offset:1280
	ds_read_b128 v[142:145], v187 offset:2560
	ds_read_b128 v[146:149], v187 offset:3840
	s_cmp_lt_u32 s37, 32
	s_cbranch_scc0 .Lret_wctx_17
	s_lshl_b32 s100, s37, 6
	s_lshl_b32 s41, s38, 5
	s_add_i32 s100, s100, s41
	v_subrev_u32_e32 v170, s100, v203
	v_subrev_u32_e32 v171, s100, v204
	v_subrev_u32_e32 v172, s100, v205
	v_subrev_u32_e32 v173, s100, v206
	v_cvt_f32_i32_e32 v174, v170
	v_cvt_f32_i32_e32 v175, v171
	v_cvt_f32_i32_e32 v176, v172
	v_cvt_f32_i32_e32 v177, v173
	v_cmp_gt_i32_e32 vcc, 0, v170
	s_nop 1
	v_cndmask_b32_e32 v178, v207, v208, vcc
	v_cmp_gt_i32_e32 vcc, 0, v171
	s_nop 1
	v_cndmask_b32_e32 v179, v207, v208, vcc
	v_cmp_gt_i32_e32 vcc, 0, v172
	s_nop 1
	v_cndmask_b32_e32 v180, v207, v208, vcc
	v_cmp_gt_i32_e32 vcc, 0, v173
	s_nop 1
	v_cndmask_b32_e32 v181, v207, v208, vcc
	v_mul_f32_e64 v178, v178, |v174|
	v_mul_f32_e64 v179, v179, |v175|
	v_mul_f32_e64 v180, v180, |v176|
	v_mul_f32_e64 v181, v181, |v177|
	v_exp_f32_e32 v166, v178
	v_exp_f32_e32 v167, v179
	v_exp_f32_e32 v168, v180
	v_exp_f32_e32 v169, v181
	s_branch .Lret_wdone_18

.Lret_wdone_18:
	s_xor_b32 s38, s38, 1
	s_cmp_eq_u32 s38, 0
	s_cselect_b32 s41, 1, 0
	s_add_i32 s37, s37, s41
	s_cmp_eq_u32 s37, 36
	s_cselect_b32 s37, 0, s37
	s_waitcnt lgkmcnt(11)
	v_mfma_f32_16x16x32_bf16 v[98:101], v[102:105], v[64:67], 0
	s_waitcnt lgkmcnt(10)
	v_mfma_f32_16x16x32_bf16 v[98:101], v[106:109], v[68:71], v[98:101]
	s_waitcnt lgkmcnt(9)
	v_mfma_f32_16x16x32_bf16 v[98:101], v[110:113], v[72:75], v[98:101]
	s_waitcnt lgkmcnt(8)
	v_mfma_f32_16x16x32_bf16 v[98:101], v[114:117], v[76:79], v[98:101]
	s_waitcnt lgkmcnt(7)
	v_mfma_f32_16x16x32_bf16 v[98:101], v[118:121], v[80:83], v[98:101]
	s_waitcnt lgkmcnt(6)
	v_mfma_f32_16x16x32_bf16 v[98:101], v[122:125], v[84:87], v[98:101]
	s_waitcnt lgkmcnt(5)
	v_mfma_f32_16x16x32_bf16 v[98:101], v[126:129], v[88:91], v[98:101]
	s_waitcnt lgkmcnt(4)
	v_mfma_f32_16x16x32_bf16 v[98:101], v[130:133], v[92:95], v[98:101]
	s_waitcnt lgkmcnt(0)
	v_mfma_f32_16x16x32_bf16 v[0:3], v[150:153], v[134:137], v[0:3]
	v_mfma_f32_16x16x32_bf16 v[16:19], v[154:157], v[134:137], v[16:19]
	v_mfma_f32_16x16x32_bf16 v[32:35], v[158:161], v[134:137], v[32:35]
	v_mfma_f32_16x16x32_bf16 v[48:51], v[162:165], v[134:137], v[48:51]
	v_mfma_f32_16x16x32_bf16 v[4:7], v[150:153], v[138:141], v[4:7]
	v_mfma_f32_16x16x32_bf16 v[20:23], v[154:157], v[138:141], v[20:23]
	v_mfma_f32_16x16x32_bf16 v[36:39], v[158:161], v[138:141], v[36:39]
	v_mfma_f32_16x16x32_bf16 v[52:55], v[162:165], v[138:141], v[52:55]
	v_mfma_f32_16x16x32_bf16 v[8:11], v[150:153], v[142:145], v[8:11]
	v_mfma_f32_16x16x32_bf16 v[24:27], v[154:157], v[142:145], v[24:27]
	v_mfma_f32_16x16x32_bf16 v[40:43], v[158:161], v[142:145], v[40:43]
	v_mfma_f32_16x16x32_bf16 v[56:59], v[162:165], v[142:145], v[56:59]
	v_mfma_f32_16x16x32_bf16 v[12:15], v[150:153], v[146:149], v[12:15]
	v_mfma_f32_16x16x32_bf16 v[28:31], v[154:157], v[146:149], v[28:31]
	v_mfma_f32_16x16x32_bf16 v[44:47], v[158:161], v[146:149], v[44:47]
	v_mfma_f32_16x16x32_bf16 v[60:63], v[162:165], v[146:149], v[60:63]
	v_mul_f32_e32 v170, v98, v166
	v_mul_f32_e32 v171, v99, v167
	v_mul_f32_e32 v172, v100, v168
	v_mul_f32_e32 v173, v101, v169
	v_cvt_pk_bf16_f32 v174, v170, v171
	v_cvt_pk_bf16_f32 v175, v172, v173
	ds_write_b64 v188, v[174:175] offset:5120
	s_waitcnt vmcnt(6)
	ds_read_b64_tr_b16 v[150:151], v183 offset:4096
	ds_read_b64_tr_b16 v[152:153], v183 offset:4608
	ds_read_b64_tr_b16 v[154:155], v184 offset:4096
	ds_read_b64_tr_b16 v[156:157], v184 offset:4608
	ds_read_b64_tr_b16 v[158:159], v185 offset:4096
	ds_read_b64_tr_b16 v[160:161], v185 offset:4608
	ds_read_b64_tr_b16 v[162:163], v186 offset:4096
	ds_read_b64_tr_b16 v[164:165], v186 offset:4608
	s_waitcnt lgkmcnt(8)
	s_barrier
	s_cmp_lt_u32 s29, 32
	s_cbranch_scc0 .Lret_dctx_19
	s_mul_i32 s41, s29, 0xc0000
	s_mul_i32 s46, s31, 0x60000
	s_add_u32 s42, s78, s41
	s_addc_u32 s43, s79, 0
	s_add_u32 s42, s42, s46
	s_addc_u32 s43, s43, 0
	s_add_i32 m0, s54, 16896
	s_nop 0
	global_load_lds_dwordx4 v189, s[42:43]
	s_add_i32 m0, s54, 17952
	s_nop 0
	global_load_lds_dwordx4 v190, s[42:43]
	s_branch .Lret_ddone_20

.Lret_ddone_22:
	s_xor_b32 s36, s36, 1
	s_cmp_eq_u32 s36, 0
	s_cselect_b32 s41, 1, 0
	s_add_i32 s34, s34, s41
	s_cmp_eq_u32 s34, 36
	s_cselect_b32 s34, 0, s34
	ds_read_b128 v[102:105], v182 offset:33792
	ds_read_b128 v[106:109], v182 offset:33856
	ds_read_b128 v[110:113], v182 offset:33920
	ds_read_b128 v[114:117], v182 offset:33984
	ds_read_b128 v[118:121], v182 offset:34048
	ds_read_b128 v[122:125], v182 offset:34112
	ds_read_b128 v[126:129], v182 offset:34176
	ds_read_b128 v[130:133], v182 offset:34240
	ds_read_b128 v[134:137], v187 offset:5120
	ds_read_b128 v[138:141], v187 offset:6400
	ds_read_b128 v[142:145], v187 offset:7680
	ds_read_b128 v[146:149], v187 offset:8960
	s_cmp_lt_u32 s37, 32
	s_cbranch_scc0 .Lret_wctx_23
	s_lshl_b32 s100, s37, 6
	s_lshl_b32 s41, s38, 5
	s_add_i32 s100, s100, s41
	v_subrev_u32_e32 v170, s100, v203
	v_subrev_u32_e32 v171, s100, v204
	v_subrev_u32_e32 v172, s100, v205
	v_subrev_u32_e32 v173, s100, v206
	v_cvt_f32_i32_e32 v174, v170
	v_cvt_f32_i32_e32 v175, v171
	v_cvt_f32_i32_e32 v176, v172
	v_cvt_f32_i32_e32 v177, v173
	v_cmp_gt_i32_e32 vcc, 0, v170
	s_nop 1
	v_cndmask_b32_e32 v178, v207, v208, vcc
	v_cmp_gt_i32_e32 vcc, 0, v171
	s_nop 1
	v_cndmask_b32_e32 v179, v207, v208, vcc
	v_cmp_gt_i32_e32 vcc, 0, v172
	s_nop 1
	v_cndmask_b32_e32 v180, v207, v208, vcc
	v_cmp_gt_i32_e32 vcc, 0, v173
	s_nop 1
	v_cndmask_b32_e32 v181, v207, v208, vcc
	v_mul_f32_e64 v178, v178, |v174|
	v_mul_f32_e64 v179, v179, |v175|
	v_mul_f32_e64 v180, v180, |v176|
	v_mul_f32_e64 v181, v181, |v177|
	v_exp_f32_e32 v166, v178
	v_exp_f32_e32 v167, v179
	v_exp_f32_e32 v168, v180
	v_exp_f32_e32 v169, v181
	s_branch .Lret_wdone_24

; #define RET_BAR() do { asm volatile("s_waitcnt lgkmcnt(0)" ::: "memory"); __builtin_amdgcn_s_barrier(); asm volatile("" ::: "memory"); } while (0)
; #define RET_LOADV(t) do { RET_KV(t) const char* vb_ = kb_ + (1024 + h * 256) * 2; const unsigned lo_ = (unsigned)(tid >> 6) * kp_ + (unsigned)(tid & 63) * 16u; \
;         _Pragma("unroll") for (int i_ = 0; i_ < 8; ++i_) vr[i_] = *(const u32x4*)(vb_ + (size_t)(8u * i_) * kp_ + lo_); } while (0)
; #define RET_STOREV() do { _Pragma("unroll") for (int i_ = 0; i_ < 8; ++i_) *(LAS u32x4*)(Vs + ((tid >> 6) + 8 * i_) * 1040 + (tid & 63) * 16) = vr[i_]; } while (0)
; __device__ __forceinline__ void ret_unit(ldsp lds, bf16_t* R, const bf16_t* RC, int b, int h, int qblk, float lgf2, float lgb2, const int tid_in) {
;     ...
;     f32x4 o[4][4];
; #pragma unroll
;     for (int db = 0; db < 4; ++db)
; #pragma unroll
;         for (int q4 = 0; q4 < 4; ++q4) o[db][q4] = (f32x4){0.f, 0.f, 0.f, 0.f};
;     ...
;     { const int tid = tid_outer, lane = tid & 63, l15 = lane & 15, lg = lane >> 4;
;       RET_BAR();
;       RET_DMAK(TI(0), 0); RET_DMAK(TI(1), 1); RET_LOADV(TI(0));
;       asm volatile("s_waitcnt vmcnt(0)" ::: "memory");
;       RET_STOREV();
;       RET_BAR();
;       RET_S(0, TI(0));
;       RET_LOADV(TI(1));
;       RET_BAR();
;       RET_DMAK(TI(2), 0); }
;     for (int t = 0; t < 36; ++t) {
;         int tl_ = tid_outer; asm volatile("" : "+v"(tl_));
;         const int tid = tl_, lane = tid & 63, l15 = lane & 15, lg = lane >> 4;
;         if (wid < 4) { RET_PV(t); if (t + 1 < 36) RET_S(t + 1, TI(t + 1)); }
;         else { if (t + 1 < 36) RET_S(t + 1, TI(t + 1)); RET_PV(t); }
;         RET_BAR();
;         asm volatile("s_waitcnt vmcnt(0)" ::: "memory");
;         if (t + 1 < 36) RET_STOREV();
;         if (t + 2 < 36) RET_LOADV(TI(t + 2));
;         if (t + 3 < 36) RET_DMAK(TI(t + 3), (t + 1) & 1);
;         RET_BAR();
.Lret_wdone_24:
	s_xor_b32 s38, s38, 1
	s_cmp_eq_u32 s38, 0
	s_cselect_b32 s41, 1, 0
	s_add_i32 s37, s37, s41
	s_cmp_eq_u32 s37, 36
	s_cselect_b32 s37, 0, s37
	s_waitcnt lgkmcnt(11)
	v_mfma_f32_16x16x32_bf16 v[98:101], v[102:105], v[64:67], 0
	s_waitcnt lgkmcnt(10)
	v_mfma_f32_16x16x32_bf16 v[98:101], v[106:109], v[68:71], v[98:101]
	s_waitcnt lgkmcnt(9)
	v_mfma_f32_16x16x32_bf16 v[98:101], v[110:113], v[72:75], v[98:101]
	s_waitcnt lgkmcnt(8)
	v_mfma_f32_16x16x32_bf16 v[98:101], v[114:117], v[76:79], v[98:101]
	s_waitcnt lgkmcnt(7)
	v_mfma_f32_16x16x32_bf16 v[98:101], v[118:121], v[80:83], v[98:101]
	s_waitcnt lgkmcnt(6)
	v_mfma_f32_16x16x32_bf16 v[98:101], v[122:125], v[84:87], v[98:101]
	s_waitcnt lgkmcnt(5)
	v_mfma_f32_16x16x32_bf16 v[98:101], v[126:129], v[88:91], v[98:101]
	s_waitcnt lgkmcnt(4)
	v_mfma_f32_16x16x32_bf16 v[98:101], v[130:133], v[92:95], v[98:101]
	s_waitcnt lgkmcnt(0)
	v_mfma_f32_16x16x32_bf16 v[0:3], v[150:153], v[134:137], v[0:3]
	v_mfma_f32_16x16x32_bf16 v[16:19], v[154:157], v[134:137], v[16:19]
	v_mfma_f32_16x16x32_bf16 v[32:35], v[158:161], v[134:137], v[32:35]
	v_mfma_f32_16x16x32_bf16 v[48:51], v[162:165], v[134:137], v[48:51]
	v_mfma_f32_16x16x32_bf16 v[4:7], v[150:153], v[138:141], v[4:7]
	v_mfma_f32_16x16x32_bf16 v[20:23], v[154:157], v[138:141], v[20:23]
	v_mfma_f32_16x16x32_bf16 v[36:39], v[158:161], v[138:141], v[36:39]
	v_mfma_f32_16x16x32_bf16 v[52:55], v[162:165], v[138:141], v[52:55]
	v_mfma_f32_16x16x32_bf16 v[8:11], v[150:153], v[142:145], v[8:11]
	v_mfma_f32_16x16x32_bf16 v[24:27], v[154:157], v[142:145], v[24:27]
	v_mfma_f32_16x16x32_bf16 v[40:43], v[158:161], v[142:145], v[40:43]
	v_mfma_f32_16x16x32_bf16 v[56:59], v[162:165], v[142:145], v[56:59]
	v_mfma_f32_16x16x32_bf16 v[12:15], v[150:153], v[146:149], v[12:15]
	v_mfma_f32_16x16x32_bf16 v[28:31], v[154:157], v[146:149], v[28:31]
	v_mfma_f32_16x16x32_bf16 v[44:47], v[158:161], v[146:149], v[44:47]
	v_mfma_f32_16x16x32_bf16 v[60:63], v[162:165], v[146:149], v[60:63]
	v_mul_f32_e32 v170, v98, v166
	v_mul_f32_e32 v171, v99, v167
	v_mul_f32_e32 v172, v100, v168
	v_mul_f32_e32 v173, v101, v169
	v_cvt_pk_bf16_f32 v174, v170, v171
	v_cvt_pk_bf16_f32 v175, v172, v173
	ds_write_b64 v188, v[174:175] offset:0
	s_waitcnt vmcnt(6)
	ds_read_b64_tr_b16 v[150:151], v183 offset:8192
	ds_read_b64_tr_b16 v[152:153], v183 offset:8704
	ds_read_b64_tr_b16 v[154:155], v184 offset:8192
	ds_read_b64_tr_b16 v[156:157], v184 offset:8704
	ds_read_b64_tr_b16 v[158:159], v185 offset:8192
	ds_read_b64_tr_b16 v[160:161], v185 offset:8704
	ds_read_b64_tr_b16 v[162:163], v186 offset:8192
	ds_read_b64_tr_b16 v[164:165], v186 offset:8704
	s_waitcnt lgkmcnt(8)
	s_barrier
	s_cmp_lt_u32 s29, 32
	s_cbranch_scc0 .Lret_dctx_25
	s_mul_i32 s41, s29, 0xc0000
	s_mul_i32 s46, s31, 0x60000
	s_add_u32 s42, s78, s41
	s_addc_u32 s43, s79, 0
	s_add_u32 s42, s42, s46
	s_addc_u32 s43, s43, 0
	s_add_i32 m0, s54, 33792
	s_nop 0
	global_load_lds_dwordx4 v189, s[42:43]
	s_add_i32 m0, s54, 34848
	s_nop 0
	global_load_lds_dwordx4 v190, s[42:43]
	s_branch .Lret_ddone_26

.Lret_ddone_26:
	s_xor_b32 s31, s31, 1
	s_cmp_eq_u32 s31, 0
	s_cselect_b32 s41, 1, 0
	s_add_i32 s29, s29, s41
	s_cmp_eq_u32 s29, 36
	s_cselect_b32 s29, 0, s29
	s_cmp_lt_u32 s34, 32
	s_cbranch_scc0 .Lret_dctx_27
	s_mul_i32 s41, s34, 0xc0000
	s_mul_i32 s46, s36, 0x60000
	s_add_u32 s44, s78, s41
	s_addc_u32 s45, s79, 0
	s_add_u32 s44, s44, s46
	s_addc_u32 s45, s45, 0
	s_add_i32 m0, s55, 4096
	s_nop 0
	global_load_lds_dwordx4 v193, s[44:45]
	s_add_i32 m0, s55, 5120
	s_nop 0
	global_load_lds_dwordx4 v194, s[44:45]
	s_add_i32 m0, s55, 6144
	s_nop 0
	global_load_lds_dwordx4 v195, s[44:45]
	s_add_i32 m0, s55, 7168
	s_nop 0
	global_load_lds_dwordx4 v197, s[44:45]
	s_branch .Lret_ddone_28

.Lret_ddone_28:
	s_xor_b32 s36, s36, 1
	s_cmp_eq_u32 s36, 0
	s_cselect_b32 s41, 1, 0
	s_add_i32 s34, s34, s41
	s_cmp_eq_u32 s34, 36
	s_cselect_b32 s34, 0, s34
	ds_read_b128 v[102:105], v182 offset:0
	ds_read_b128 v[106:109], v182 offset:64
	ds_read_b128 v[110:113], v182 offset:128
	ds_read_b128 v[114:117], v182 offset:192
	ds_read_b128 v[118:121], v182 offset:256
	ds_read_b128 v[122:125], v182 offset:320
	ds_read_b128 v[126:129], v182 offset:384
	ds_read_b128 v[130:133], v182 offset:448
	ds_read_b128 v[134:137], v187 offset:0
	ds_read_b128 v[138:141], v187 offset:1280
	ds_read_b128 v[142:145], v187 offset:2560
	ds_read_b128 v[146:149], v187 offset:3840
	s_cmp_lt_u32 s37, 32
	s_cbranch_scc0 .Lret_wctx_29
	s_lshl_b32 s100, s37, 6
	s_lshl_b32 s41, s38, 5
	s_add_i32 s100, s100, s41
	v_subrev_u32_e32 v170, s100, v203
	v_subrev_u32_e32 v171, s100, v204
	v_subrev_u32_e32 v172, s100, v205
	v_subrev_u32_e32 v173, s100, v206
	v_cvt_f32_i32_e32 v174, v170
	v_cvt_f32_i32_e32 v175, v171
	v_cvt_f32_i32_e32 v176, v172
	v_cvt_f32_i32_e32 v177, v173
	v_cmp_gt_i32_e32 vcc, 0, v170
	s_nop 1
	v_cndmask_b32_e32 v178, v207, v208, vcc
	v_cmp_gt_i32_e32 vcc, 0, v171
	s_nop 1
	v_cndmask_b32_e32 v179, v207, v208, vcc
	v_cmp_gt_i32_e32 vcc, 0, v172
	s_nop 1
	v_cndmask_b32_e32 v180, v207, v208, vcc
	v_cmp_gt_i32_e32 vcc, 0, v173
	s_nop 1
	v_cndmask_b32_e32 v181, v207, v208, vcc
	v_mul_f32_e64 v178, v178, |v174|
	v_mul_f32_e64 v179, v179, |v175|
	v_mul_f32_e64 v180, v180, |v176|
	v_mul_f32_e64 v181, v181, |v177|
	v_exp_f32_e32 v166, v178
	v_exp_f32_e32 v167, v179
	v_exp_f32_e32 v168, v180
	v_exp_f32_e32 v169, v181
	s_branch .Lret_wdone_30

; #define RET_BAR() do { asm volatile("s_waitcnt lgkmcnt(0)" ::: "memory"); __builtin_amdgcn_s_barrier(); asm volatile("" ::: "memory"); } while (0)
; #define RET_LOADV(t) do { RET_KV(t) const char* vb_ = kb_ + (1024 + h * 256) * 2; const unsigned lo_ = (unsigned)(tid >> 6) * kp_ + (unsigned)(tid & 63) * 16u; \
;         _Pragma("unroll") for (int i_ = 0; i_ < 8; ++i_) vr[i_] = *(const u32x4*)(vb_ + (size_t)(8u * i_) * kp_ + lo_); } while (0)
; #define RET_STOREV() do { _Pragma("unroll") for (int i_ = 0; i_ < 8; ++i_) *(LAS u32x4*)(Vs + ((tid >> 6) + 8 * i_) * 1040 + (tid & 63) * 16) = vr[i_]; } while (0)
; __device__ __forceinline__ void ret_unit(ldsp lds, bf16_t* R, const bf16_t* RC, int b, int h, int qblk, float lgf2, float lgb2, const int tid_in) {
;     ...
;     f32x4 o[4][4];
; #pragma unroll
;     for (int db = 0; db < 4; ++db)
; #pragma unroll
;         for (int q4 = 0; q4 < 4; ++q4) o[db][q4] = (f32x4){0.f, 0.f, 0.f, 0.f};
;     ...
;     { const int tid = tid_outer, lane = tid & 63, l15 = lane & 15, lg = lane >> 4;
;       RET_BAR();
;       RET_DMAK(TI(0), 0); RET_DMAK(TI(1), 1); RET_LOADV(TI(0));
;       asm volatile("s_waitcnt vmcnt(0)" ::: "memory");
;       RET_STOREV();
;       RET_BAR();
;       RET_S(0, TI(0));
;       RET_LOADV(TI(1));
;       RET_BAR();
;       RET_DMAK(TI(2), 0); }
;     for (int t = 0; t < 36; ++t) {
;         int tl_ = tid_outer; asm volatile("" : "+v"(tl_));
;         const int tid = tl_, lane = tid & 63, l15 = lane & 15, lg = lane >> 4;
;         if (wid < 4) { RET_PV(t); if (t + 1 < 36) RET_S(t + 1, TI(t + 1)); }
;         else { if (t + 1 < 36) RET_S(t + 1, TI(t + 1)); RET_PV(t); }
;         RET_BAR();
;         asm volatile("s_waitcnt vmcnt(0)" ::: "memory");
;         if (t + 1 < 36) RET_STOREV();
;         if (t + 2 < 36) RET_LOADV(TI(t + 2));
;         if (t + 3 < 36) RET_DMAK(TI(t + 3), (t + 1) & 1);
;         RET_BAR();
.Lret_wdone_30:
	s_xor_b32 s38, s38, 1
	s_cmp_eq_u32 s38, 0
	s_cselect_b32 s41, 1, 0
	s_add_i32 s37, s37, s41
	s_cmp_eq_u32 s37, 36
	s_cselect_b32 s37, 0, s37
	s_waitcnt lgkmcnt(11)
	v_mfma_f32_16x16x32_bf16 v[98:101], v[102:105], v[64:67], 0
	s_waitcnt lgkmcnt(10)
	v_mfma_f32_16x16x32_bf16 v[98:101], v[106:109], v[68:71], v[98:101]
	s_waitcnt lgkmcnt(9)
	v_mfma_f32_16x16x32_bf16 v[98:101], v[110:113], v[72:75], v[98:101]
	s_waitcnt lgkmcnt(8)
	v_mfma_f32_16x16x32_bf16 v[98:101], v[114:117], v[76:79], v[98:101]
	s_waitcnt lgkmcnt(7)
	v_mfma_f32_16x16x32_bf16 v[98:101], v[118:121], v[80:83], v[98:101]
	s_waitcnt lgkmcnt(6)
	v_mfma_f32_16x16x32_bf16 v[98:101], v[122:125], v[84:87], v[98:101]
	s_waitcnt lgkmcnt(5)
	v_mfma_f32_16x16x32_bf16 v[98:101], v[126:129], v[88:91], v[98:101]
	s_waitcnt lgkmcnt(4)
	v_mfma_f32_16x16x32_bf16 v[98:101], v[130:133], v[92:95], v[98:101]
	s_waitcnt lgkmcnt(0)
	v_mfma_f32_16x16x32_bf16 v[0:3], v[150:153], v[134:137], v[0:3]
	v_mfma_f32_16x16x32_bf16 v[16:19], v[154:157], v[134:137], v[16:19]
	v_mfma_f32_16x16x32_bf16 v[32:35], v[158:161], v[134:137], v[32:35]
	v_mfma_f32_16x16x32_bf16 v[48:51], v[162:165], v[134:137], v[48:51]
	v_mfma_f32_16x16x32_bf16 v[4:7], v[150:153], v[138:141], v[4:7]
	v_mfma_f32_16x16x32_bf16 v[20:23], v[154:157], v[138:141], v[20:23]
	v_mfma_f32_16x16x32_bf16 v[36:39], v[158:161], v[138:141], v[36:39]
	v_mfma_f32_16x16x32_bf16 v[52:55], v[162:165], v[138:141], v[52:55]
	v_mfma_f32_16x16x32_bf16 v[8:11], v[150:153], v[142:145], v[8:11]
	v_mfma_f32_16x16x32_bf16 v[24:27], v[154:157], v[142:145], v[24:27]
	v_mfma_f32_16x16x32_bf16 v[40:43], v[158:161], v[142:145], v[40:43]
	v_mfma_f32_16x16x32_bf16 v[56:59], v[162:165], v[142:145], v[56:59]
	v_mfma_f32_16x16x32_bf16 v[12:15], v[150:153], v[146:149], v[12:15]
	v_mfma_f32_16x16x32_bf16 v[28:31], v[154:157], v[146:149], v[28:31]
	v_mfma_f32_16x16x32_bf16 v[44:47], v[158:161], v[146:149], v[44:47]
	v_mfma_f32_16x16x32_bf16 v[60:63], v[162:165], v[146:149], v[60:63]
	v_mul_f32_e32 v170, v98, v166
	v_mul_f32_e32 v171, v99, v167
	v_mul_f32_e32 v172, v100, v168
	v_mul_f32_e32 v173, v101, v169
	v_cvt_pk_bf16_f32 v174, v170, v171
	v_cvt_pk_bf16_f32 v175, v172, v173
	ds_write_b64 v188, v[174:175] offset:5120
	s_waitcnt vmcnt(6)
	ds_read_b64_tr_b16 v[150:151], v183 offset:0
	ds_read_b64_tr_b16 v[152:153], v183 offset:512
	ds_read_b64_tr_b16 v[154:155], v184 offset:0
	ds_read_b64_tr_b16 v[156:157], v184 offset:512
	ds_read_b64_tr_b16 v[158:159], v185 offset:0
	ds_read_b64_tr_b16 v[160:161], v185 offset:512
	ds_read_b64_tr_b16 v[162:163], v186 offset:0
	ds_read_b64_tr_b16 v[164:165], v186 offset:512
	s_waitcnt lgkmcnt(8)
	s_barrier
	s_cmp_lt_u32 s29, 32
	s_cbranch_scc0 .Lret_dctx_31
	s_mul_i32 s41, s29, 0xc0000
	s_mul_i32 s46, s31, 0x60000
	s_add_u32 s42, s78, s41
	s_addc_u32 s43, s79, 0
	s_add_u32 s42, s42, s46
	s_addc_u32 s43, s43, 0
	s_add_i32 m0, s54, 0
	s_nop 0
	global_load_lds_dwordx4 v189, s[42:43]
	s_add_i32 m0, s54, 1056
	s_nop 0
	global_load_lds_dwordx4 v190, s[42:43]
	s_branch .Lret_ddone_32

.Lret_ddone_34:
	s_xor_b32 s36, s36, 1
	s_cmp_eq_u32 s36, 0
	s_cselect_b32 s41, 1, 0
	s_add_i32 s34, s34, s41
	s_cmp_eq_u32 s34, 36
	s_cselect_b32 s34, 0, s34
	ds_read_b128 v[102:105], v182 offset:16896
	ds_read_b128 v[106:109], v182 offset:16960
	ds_read_b128 v[110:113], v182 offset:17024
	ds_read_b128 v[114:117], v182 offset:17088
	ds_read_b128 v[118:121], v182 offset:17152
	ds_read_b128 v[122:125], v182 offset:17216
	ds_read_b128 v[126:129], v182 offset:17280
	ds_read_b128 v[130:133], v182 offset:17344
	ds_read_b128 v[134:137], v187 offset:5120
	ds_read_b128 v[138:141], v187 offset:6400
	ds_read_b128 v[142:145], v187 offset:7680
	ds_read_b128 v[146:149], v187 offset:8960
	s_cmp_lt_u32 s37, 32
	s_cbranch_scc0 .Lret_wctx_35
	s_lshl_b32 s100, s37, 6
	s_lshl_b32 s41, s38, 5
	s_add_i32 s100, s100, s41
	v_subrev_u32_e32 v170, s100, v203
	v_subrev_u32_e32 v171, s100, v204
	v_subrev_u32_e32 v172, s100, v205
	v_subrev_u32_e32 v173, s100, v206
	v_cvt_f32_i32_e32 v174, v170
	v_cvt_f32_i32_e32 v175, v171
	v_cvt_f32_i32_e32 v176, v172
	v_cvt_f32_i32_e32 v177, v173
	v_cmp_gt_i32_e32 vcc, 0, v170
	s_nop 1
	v_cndmask_b32_e32 v178, v207, v208, vcc
	v_cmp_gt_i32_e32 vcc, 0, v171
	s_nop 1
	v_cndmask_b32_e32 v179, v207, v208, vcc
	v_cmp_gt_i32_e32 vcc, 0, v172
	s_nop 1
	v_cndmask_b32_e32 v180, v207, v208, vcc
	v_cmp_gt_i32_e32 vcc, 0, v173
	s_nop 1
	v_cndmask_b32_e32 v181, v207, v208, vcc
	v_mul_f32_e64 v178, v178, |v174|
	v_mul_f32_e64 v179, v179, |v175|
	v_mul_f32_e64 v180, v180, |v176|
	v_mul_f32_e64 v181, v181, |v177|
	v_exp_f32_e32 v166, v178
	v_exp_f32_e32 v167, v179
	v_exp_f32_e32 v168, v180
	v_exp_f32_e32 v169, v181
	s_branch .Lret_wdone_36

; #define RET_BAR() do { asm volatile("s_waitcnt lgkmcnt(0)" ::: "memory"); __builtin_amdgcn_s_barrier(); asm volatile("" ::: "memory"); } while (0)
; #define RET_LOADV(t) do { RET_KV(t) const char* vb_ = kb_ + (1024 + h * 256) * 2; const unsigned lo_ = (unsigned)(tid >> 6) * kp_ + (unsigned)(tid & 63) * 16u; \
;         _Pragma("unroll") for (int i_ = 0; i_ < 8; ++i_) vr[i_] = *(const u32x4*)(vb_ + (size_t)(8u * i_) * kp_ + lo_); } while (0)
; #define RET_STOREV() do { _Pragma("unroll") for (int i_ = 0; i_ < 8; ++i_) *(LAS u32x4*)(Vs + ((tid >> 6) + 8 * i_) * 1040 + (tid & 63) * 16) = vr[i_]; } while (0)
; __device__ __forceinline__ void ret_unit(ldsp lds, bf16_t* R, const bf16_t* RC, int b, int h, int qblk, float lgf2, float lgb2, const int tid_in) {
;     ...
;     f32x4 o[4][4];
; #pragma unroll
;     for (int db = 0; db < 4; ++db)
; #pragma unroll
;         for (int q4 = 0; q4 < 4; ++q4) o[db][q4] = (f32x4){0.f, 0.f, 0.f, 0.f};
;     ...
;     { const int tid = tid_outer, lane = tid & 63, l15 = lane & 15, lg = lane >> 4;
;       RET_BAR();
;       RET_DMAK(TI(0), 0); RET_DMAK(TI(1), 1); RET_LOADV(TI(0));
;       asm volatile("s_waitcnt vmcnt(0)" ::: "memory");
;       RET_STOREV();
;       RET_BAR();
;       RET_S(0, TI(0));
;       RET_LOADV(TI(1));
;       RET_BAR();
;       RET_DMAK(TI(2), 0); }
;     for (int t = 0; t < 36; ++t) {
;         int tl_ = tid_outer; asm volatile("" : "+v"(tl_));
;         const int tid = tl_, lane = tid & 63, l15 = lane & 15, lg = lane >> 4;
;         if (wid < 4) { RET_PV(t); if (t + 1 < 36) RET_S(t + 1, TI(t + 1)); }
;         else { if (t + 1 < 36) RET_S(t + 1, TI(t + 1)); RET_PV(t); }
;         RET_BAR();
;         asm volatile("s_waitcnt vmcnt(0)" ::: "memory");
;         if (t + 1 < 36) RET_STOREV();
;         if (t + 2 < 36) RET_LOADV(TI(t + 2));
;         if (t + 3 < 36) RET_DMAK(TI(t + 3), (t + 1) & 1);
;         RET_BAR();
.Lret_wdone_36:
	s_xor_b32 s38, s38, 1
	s_cmp_eq_u32 s38, 0
	s_cselect_b32 s41, 1, 0
	s_add_i32 s37, s37, s41
	s_cmp_eq_u32 s37, 36
	s_cselect_b32 s37, 0, s37
	s_waitcnt lgkmcnt(11)
	v_mfma_f32_16x16x32_bf16 v[98:101], v[102:105], v[64:67], 0
	s_waitcnt lgkmcnt(10)
	v_mfma_f32_16x16x32_bf16 v[98:101], v[106:109], v[68:71], v[98:101]
	s_waitcnt lgkmcnt(9)
	v_mfma_f32_16x16x32_bf16 v[98:101], v[110:113], v[72:75], v[98:101]
	s_waitcnt lgkmcnt(8)
	v_mfma_f32_16x16x32_bf16 v[98:101], v[114:117], v[76:79], v[98:101]
	s_waitcnt lgkmcnt(7)
	v_mfma_f32_16x16x32_bf16 v[98:101], v[118:121], v[80:83], v[98:101]
	s_waitcnt lgkmcnt(6)
	v_mfma_f32_16x16x32_bf16 v[98:101], v[122:125], v[84:87], v[98:101]
	s_waitcnt lgkmcnt(5)
	v_mfma_f32_16x16x32_bf16 v[98:101], v[126:129], v[88:91], v[98:101]
	s_waitcnt lgkmcnt(4)
	v_mfma_f32_16x16x32_bf16 v[98:101], v[130:133], v[92:95], v[98:101]
	s_waitcnt lgkmcnt(0)
	v_mfma_f32_16x16x32_bf16 v[0:3], v[150:153], v[134:137], v[0:3]
	v_mfma_f32_16x16x32_bf16 v[16:19], v[154:157], v[134:137], v[16:19]
	v_mfma_f32_16x16x32_bf16 v[32:35], v[158:161], v[134:137], v[32:35]
	v_mfma_f32_16x16x32_bf16 v[48:51], v[162:165], v[134:137], v[48:51]
	v_mfma_f32_16x16x32_bf16 v[4:7], v[150:153], v[138:141], v[4:7]
	v_mfma_f32_16x16x32_bf16 v[20:23], v[154:157], v[138:141], v[20:23]
	v_mfma_f32_16x16x32_bf16 v[36:39], v[158:161], v[138:141], v[36:39]
	v_mfma_f32_16x16x32_bf16 v[52:55], v[162:165], v[138:141], v[52:55]
	v_mfma_f32_16x16x32_bf16 v[8:11], v[150:153], v[142:145], v[8:11]
	v_mfma_f32_16x16x32_bf16 v[24:27], v[154:157], v[142:145], v[24:27]
	v_mfma_f32_16x16x32_bf16 v[40:43], v[158:161], v[142:145], v[40:43]
	v_mfma_f32_16x16x32_bf16 v[56:59], v[162:165], v[142:145], v[56:59]
	v_mfma_f32_16x16x32_bf16 v[12:15], v[150:153], v[146:149], v[12:15]
	v_mfma_f32_16x16x32_bf16 v[28:31], v[154:157], v[146:149], v[28:31]
	v_mfma_f32_16x16x32_bf16 v[44:47], v[158:161], v[146:149], v[44:47]
	v_mfma_f32_16x16x32_bf16 v[60:63], v[162:165], v[146:149], v[60:63]
	v_mul_f32_e32 v170, v98, v166
	v_mul_f32_e32 v171, v99, v167
	v_mul_f32_e32 v172, v100, v168
	v_mul_f32_e32 v173, v101, v169
	v_cvt_pk_bf16_f32 v174, v170, v171
	v_cvt_pk_bf16_f32 v175, v172, v173
	ds_write_b64 v188, v[174:175] offset:0
	s_waitcnt vmcnt(6)
	ds_read_b64_tr_b16 v[150:151], v183 offset:4096
	ds_read_b64_tr_b16 v[152:153], v183 offset:4608
	ds_read_b64_tr_b16 v[154:155], v184 offset:4096
	ds_read_b64_tr_b16 v[156:157], v184 offset:4608
	ds_read_b64_tr_b16 v[158:159], v185 offset:4096
	ds_read_b64_tr_b16 v[160:161], v185 offset:4608
	ds_read_b64_tr_b16 v[162:163], v186 offset:4096
	ds_read_b64_tr_b16 v[164:165], v186 offset:4608
	s_waitcnt lgkmcnt(8)
	s_barrier
	s_cmp_lt_u32 s29, 32
	s_cbranch_scc0 .Lret_dctx_37
	s_mul_i32 s41, s29, 0xc0000
	s_mul_i32 s46, s31, 0x60000
	s_add_u32 s42, s78, s41
	s_addc_u32 s43, s79, 0
	s_add_u32 s42, s42, s46
	s_addc_u32 s43, s43, 0
	s_add_i32 m0, s54, 16896
	s_nop 0
	global_load_lds_dwordx4 v189, s[42:43]
	s_add_i32 m0, s54, 17952
	s_nop 0
	global_load_lds_dwordx4 v190, s[42:43]
	s_branch .Lret_ddone_38

.Lret_ddone_40:
	s_xor_b32 s36, s36, 1
	s_cmp_eq_u32 s36, 0
	s_cselect_b32 s41, 1, 0
	s_add_i32 s34, s34, s41
	s_cmp_eq_u32 s34, 36
	s_cselect_b32 s34, 0, s34
	ds_read_b128 v[102:105], v182 offset:33792
	ds_read_b128 v[106:109], v182 offset:33856
	ds_read_b128 v[110:113], v182 offset:33920
	ds_read_b128 v[114:117], v182 offset:33984
	ds_read_b128 v[118:121], v182 offset:34048
	ds_read_b128 v[122:125], v182 offset:34112
	ds_read_b128 v[126:129], v182 offset:34176
	ds_read_b128 v[130:133], v182 offset:34240
	ds_read_b128 v[134:137], v187 offset:0
	ds_read_b128 v[138:141], v187 offset:1280
	ds_read_b128 v[142:145], v187 offset:2560
	ds_read_b128 v[146:149], v187 offset:3840
	s_cmp_lt_u32 s37, 32
	s_cbranch_scc0 .Lret_wctx_41
	s_lshl_b32 s100, s37, 6
	s_lshl_b32 s41, s38, 5
	s_add_i32 s100, s100, s41
	v_subrev_u32_e32 v170, s100, v203
	v_subrev_u32_e32 v171, s100, v204
	v_subrev_u32_e32 v172, s100, v205
	v_subrev_u32_e32 v173, s100, v206
	v_cvt_f32_i32_e32 v174, v170
	v_cvt_f32_i32_e32 v175, v171
	v_cvt_f32_i32_e32 v176, v172
	v_cvt_f32_i32_e32 v177, v173
	v_cmp_gt_i32_e32 vcc, 0, v170
	s_nop 1
	v_cndmask_b32_e32 v178, v207, v208, vcc
	v_cmp_gt_i32_e32 vcc, 0, v171
	s_nop 1
	v_cndmask_b32_e32 v179, v207, v208, vcc
	v_cmp_gt_i32_e32 vcc, 0, v172
	s_nop 1
	v_cndmask_b32_e32 v180, v207, v208, vcc
	v_cmp_gt_i32_e32 vcc, 0, v173
	s_nop 1
	v_cndmask_b32_e32 v181, v207, v208, vcc
	v_mul_f32_e64 v178, v178, |v174|
	v_mul_f32_e64 v179, v179, |v175|
	v_mul_f32_e64 v180, v180, |v176|
	v_mul_f32_e64 v181, v181, |v177|
	v_exp_f32_e32 v166, v178
	v_exp_f32_e32 v167, v179
	v_exp_f32_e32 v168, v180
	v_exp_f32_e32 v169, v181
	s_branch .Lret_wdone_42

; #define RET_BAR() do { asm volatile("s_waitcnt lgkmcnt(0)" ::: "memory"); __builtin_amdgcn_s_barrier(); asm volatile("" ::: "memory"); } while (0)
; #define RET_LOADV(t) do { RET_KV(t) const char* vb_ = kb_ + (1024 + h * 256) * 2; const unsigned lo_ = (unsigned)(tid >> 6) * kp_ + (unsigned)(tid & 63) * 16u; \
;         _Pragma("unroll") for (int i_ = 0; i_ < 8; ++i_) vr[i_] = *(const u32x4*)(vb_ + (size_t)(8u * i_) * kp_ + lo_); } while (0)
; #define RET_STOREV() do { _Pragma("unroll") for (int i_ = 0; i_ < 8; ++i_) *(LAS u32x4*)(Vs + ((tid >> 6) + 8 * i_) * 1040 + (tid & 63) * 16) = vr[i_]; } while (0)
; __device__ __forceinline__ void ret_unit(ldsp lds, bf16_t* R, const bf16_t* RC, int b, int h, int qblk, float lgf2, float lgb2, const int tid_in) {
;     ...
;     f32x4 o[4][4];
; #pragma unroll
;     for (int db = 0; db < 4; ++db)
; #pragma unroll
;         for (int q4 = 0; q4 < 4; ++q4) o[db][q4] = (f32x4){0.f, 0.f, 0.f, 0.f};
;     ...
;     { const int tid = tid_outer, lane = tid & 63, l15 = lane & 15, lg = lane >> 4;
;       RET_BAR();
;       RET_DMAK(TI(0), 0); RET_DMAK(TI(1), 1); RET_LOADV(TI(0));
;       asm volatile("s_waitcnt vmcnt(0)" ::: "memory");
;       RET_STOREV();
;       RET_BAR();
;       RET_S(0, TI(0));
;       RET_LOADV(TI(1));
;       RET_BAR();
;       RET_DMAK(TI(2), 0); }
;     for (int t = 0; t < 36; ++t) {
;         int tl_ = tid_outer; asm volatile("" : "+v"(tl_));
;         const int tid = tl_, lane = tid & 63, l15 = lane & 15, lg = lane >> 4;
;         if (wid < 4) { RET_PV(t); if (t + 1 < 36) RET_S(t + 1, TI(t + 1)); }
;         else { if (t + 1 < 36) RET_S(t + 1, TI(t + 1)); RET_PV(t); }
;         RET_BAR();
;         asm volatile("s_waitcnt vmcnt(0)" ::: "memory");
;         if (t + 1 < 36) RET_STOREV();
;         if (t + 2 < 36) RET_LOADV(TI(t + 2));
;         if (t + 3 < 36) RET_DMAK(TI(t + 3), (t + 1) & 1);
;         RET_BAR();
.Lret_wdone_42:
	s_xor_b32 s38, s38, 1
	s_cmp_eq_u32 s38, 0
	s_cselect_b32 s41, 1, 0
	s_add_i32 s37, s37, s41
	s_cmp_eq_u32 s37, 36
	s_cselect_b32 s37, 0, s37
	s_waitcnt lgkmcnt(11)
	v_mfma_f32_16x16x32_bf16 v[98:101], v[102:105], v[64:67], 0
	s_waitcnt lgkmcnt(10)
	v_mfma_f32_16x16x32_bf16 v[98:101], v[106:109], v[68:71], v[98:101]
	s_waitcnt lgkmcnt(9)
	v_mfma_f32_16x16x32_bf16 v[98:101], v[110:113], v[72:75], v[98:101]
	s_waitcnt lgkmcnt(8)
	v_mfma_f32_16x16x32_bf16 v[98:101], v[114:117], v[76:79], v[98:101]
	s_waitcnt lgkmcnt(7)
	v_mfma_f32_16x16x32_bf16 v[98:101], v[118:121], v[80:83], v[98:101]
	s_waitcnt lgkmcnt(6)
	v_mfma_f32_16x16x32_bf16 v[98:101], v[122:125], v[84:87], v[98:101]
	s_waitcnt lgkmcnt(5)
	v_mfma_f32_16x16x32_bf16 v[98:101], v[126:129], v[88:91], v[98:101]
	s_waitcnt lgkmcnt(4)
	v_mfma_f32_16x16x32_bf16 v[98:101], v[130:133], v[92:95], v[98:101]
	s_waitcnt lgkmcnt(0)
	v_mfma_f32_16x16x32_bf16 v[0:3], v[150:153], v[134:137], v[0:3]
	v_mfma_f32_16x16x32_bf16 v[16:19], v[154:157], v[134:137], v[16:19]
	v_mfma_f32_16x16x32_bf16 v[32:35], v[158:161], v[134:137], v[32:35]
	v_mfma_f32_16x16x32_bf16 v[48:51], v[162:165], v[134:137], v[48:51]
	v_mfma_f32_16x16x32_bf16 v[4:7], v[150:153], v[138:141], v[4:7]
	v_mfma_f32_16x16x32_bf16 v[20:23], v[154:157], v[138:141], v[20:23]
	v_mfma_f32_16x16x32_bf16 v[36:39], v[158:161], v[138:141], v[36:39]
	v_mfma_f32_16x16x32_bf16 v[52:55], v[162:165], v[138:141], v[52:55]
	v_mfma_f32_16x16x32_bf16 v[8:11], v[150:153], v[142:145], v[8:11]
	v_mfma_f32_16x16x32_bf16 v[24:27], v[154:157], v[142:145], v[24:27]
	v_mfma_f32_16x16x32_bf16 v[40:43], v[158:161], v[142:145], v[40:43]
	v_mfma_f32_16x16x32_bf16 v[56:59], v[162:165], v[142:145], v[56:59]
	v_mfma_f32_16x16x32_bf16 v[12:15], v[150:153], v[146:149], v[12:15]
	v_mfma_f32_16x16x32_bf16 v[28:31], v[154:157], v[146:149], v[28:31]
	v_mfma_f32_16x16x32_bf16 v[44:47], v[158:161], v[146:149], v[44:47]
	v_mfma_f32_16x16x32_bf16 v[60:63], v[162:165], v[146:149], v[60:63]
	v_mul_f32_e32 v170, v98, v166
	v_mul_f32_e32 v171, v99, v167
	v_mul_f32_e32 v172, v100, v168
	v_mul_f32_e32 v173, v101, v169
	v_cvt_pk_bf16_f32 v174, v170, v171
	v_cvt_pk_bf16_f32 v175, v172, v173
	ds_write_b64 v188, v[174:175] offset:5120
	s_waitcnt vmcnt(6)
	ds_read_b64_tr_b16 v[150:151], v183 offset:8192
	ds_read_b64_tr_b16 v[152:153], v183 offset:8704
	ds_read_b64_tr_b16 v[154:155], v184 offset:8192
	ds_read_b64_tr_b16 v[156:157], v184 offset:8704
	ds_read_b64_tr_b16 v[158:159], v185 offset:8192
	ds_read_b64_tr_b16 v[160:161], v185 offset:8704
	ds_read_b64_tr_b16 v[162:163], v186 offset:8192
	ds_read_b64_tr_b16 v[164:165], v186 offset:8704
	s_waitcnt lgkmcnt(8)
	s_barrier
	s_cmp_lt_u32 s29, 32
	s_cbranch_scc0 .Lret_dctx_43
	s_mul_i32 s41, s29, 0xc0000
	s_mul_i32 s46, s31, 0x60000
	s_add_u32 s42, s78, s41
	s_addc_u32 s43, s79, 0
	s_add_u32 s42, s42, s46
	s_addc_u32 s43, s43, 0
	s_add_i32 m0, s54, 33792
	s_nop 0
	global_load_lds_dwordx4 v189, s[42:43]
	s_add_i32 m0, s54, 34848
	s_nop 0
	global_load_lds_dwordx4 v190, s[42:43]
	s_branch .Lret_ddone_44

.Lret_ddone_46:
	s_xor_b32 s36, s36, 1
	s_cmp_eq_u32 s36, 0
	s_cselect_b32 s41, 1, 0
	s_add_i32 s34, s34, s41
	s_cmp_eq_u32 s34, 36
	s_cselect_b32 s34, 0, s34
	ds_read_b128 v[102:105], v182 offset:0
	ds_read_b128 v[106:109], v182 offset:64
	ds_read_b128 v[110:113], v182 offset:128
	ds_read_b128 v[114:117], v182 offset:192
	ds_read_b128 v[118:121], v182 offset:256
	ds_read_b128 v[122:125], v182 offset:320
	ds_read_b128 v[126:129], v182 offset:384
	ds_read_b128 v[130:133], v182 offset:448
	ds_read_b128 v[134:137], v187 offset:5120
	ds_read_b128 v[138:141], v187 offset:6400
	ds_read_b128 v[142:145], v187 offset:7680
	ds_read_b128 v[146:149], v187 offset:8960
	s_cmp_lt_u32 s37, 32
	s_cbranch_scc0 .Lret_wctx_47
	s_lshl_b32 s100, s37, 6
	s_lshl_b32 s41, s38, 5
	s_add_i32 s100, s100, s41
	v_subrev_u32_e32 v170, s100, v203
	v_subrev_u32_e32 v171, s100, v204
	v_subrev_u32_e32 v172, s100, v205
	v_subrev_u32_e32 v173, s100, v206
	v_cvt_f32_i32_e32 v174, v170
	v_cvt_f32_i32_e32 v175, v171
	v_cvt_f32_i32_e32 v176, v172
	v_cvt_f32_i32_e32 v177, v173
	v_cmp_gt_i32_e32 vcc, 0, v170
	s_nop 1
	v_cndmask_b32_e32 v178, v207, v208, vcc
	v_cmp_gt_i32_e32 vcc, 0, v171
	s_nop 1
	v_cndmask_b32_e32 v179, v207, v208, vcc
	v_cmp_gt_i32_e32 vcc, 0, v172
	s_nop 1
	v_cndmask_b32_e32 v180, v207, v208, vcc
	v_cmp_gt_i32_e32 vcc, 0, v173
	s_nop 1
	v_cndmask_b32_e32 v181, v207, v208, vcc
	v_mul_f32_e64 v178, v178, |v174|
	v_mul_f32_e64 v179, v179, |v175|
	v_mul_f32_e64 v180, v180, |v176|
	v_mul_f32_e64 v181, v181, |v177|
	v_exp_f32_e32 v166, v178
	v_exp_f32_e32 v167, v179
	v_exp_f32_e32 v168, v180
	v_exp_f32_e32 v169, v181
	s_branch .Lret_wdone_48

; #define RET_BAR() do { asm volatile("s_waitcnt lgkmcnt(0)" ::: "memory"); __builtin_amdgcn_s_barrier(); asm volatile("" ::: "memory"); } while (0)
; #define RET_LOADV(t) do { RET_KV(t) const char* vb_ = kb_ + (1024 + h * 256) * 2; const unsigned lo_ = (unsigned)(tid >> 6) * kp_ + (unsigned)(tid & 63) * 16u; \
;         _Pragma("unroll") for (int i_ = 0; i_ < 8; ++i_) vr[i_] = *(const u32x4*)(vb_ + (size_t)(8u * i_) * kp_ + lo_); } while (0)
; #define RET_STOREV() do { _Pragma("unroll") for (int i_ = 0; i_ < 8; ++i_) *(LAS u32x4*)(Vs + ((tid >> 6) + 8 * i_) * 1040 + (tid & 63) * 16) = vr[i_]; } while (0)
; __device__ __forceinline__ void ret_unit(ldsp lds, bf16_t* R, const bf16_t* RC, int b, int h, int qblk, float lgf2, float lgb2, const int tid_in) {
;     ...
;     f32x4 o[4][4];
; #pragma unroll
;     for (int db = 0; db < 4; ++db)
; #pragma unroll
;         for (int q4 = 0; q4 < 4; ++q4) o[db][q4] = (f32x4){0.f, 0.f, 0.f, 0.f};
;     ...
;     { const int tid = tid_outer, lane = tid & 63, l15 = lane & 15, lg = lane >> 4;
;       RET_BAR();
;       RET_DMAK(TI(0), 0); RET_DMAK(TI(1), 1); RET_LOADV(TI(0));
;       asm volatile("s_waitcnt vmcnt(0)" ::: "memory");
;       RET_STOREV();
;       RET_BAR();
;       RET_S(0, TI(0));
;       RET_LOADV(TI(1));
;       RET_BAR();
;       RET_DMAK(TI(2), 0); }
;     for (int t = 0; t < 36; ++t) {
;         int tl_ = tid_outer; asm volatile("" : "+v"(tl_));
;         const int tid = tl_, lane = tid & 63, l15 = lane & 15, lg = lane >> 4;
;         if (wid < 4) { RET_PV(t); if (t + 1 < 36) RET_S(t + 1, TI(t + 1)); }
;         else { if (t + 1 < 36) RET_S(t + 1, TI(t + 1)); RET_PV(t); }
;         RET_BAR();
;         asm volatile("s_waitcnt vmcnt(0)" ::: "memory");
;         if (t + 1 < 36) RET_STOREV();
;         if (t + 2 < 36) RET_LOADV(TI(t + 2));
;         if (t + 3 < 36) RET_DMAK(TI(t + 3), (t + 1) & 1);
;         RET_BAR();
;     }
.Lret_wdone_48:
	s_xor_b32 s38, s38, 1
	s_cmp_eq_u32 s38, 0
	s_cselect_b32 s41, 1, 0
	s_add_i32 s37, s37, s41
	s_cmp_eq_u32 s37, 36
	s_cselect_b32 s37, 0, s37
	s_waitcnt lgkmcnt(11)
	v_mfma_f32_16x16x32_bf16 v[98:101], v[102:105], v[64:67], 0
	s_waitcnt lgkmcnt(10)
	v_mfma_f32_16x16x32_bf16 v[98:101], v[106:109], v[68:71], v[98:101]
	s_waitcnt lgkmcnt(9)
	v_mfma_f32_16x16x32_bf16 v[98:101], v[110:113], v[72:75], v[98:101]
	s_waitcnt lgkmcnt(8)
	v_mfma_f32_16x16x32_bf16 v[98:101], v[114:117], v[76:79], v[98:101]
	s_waitcnt lgkmcnt(7)
	v_mfma_f32_16x16x32_bf16 v[98:101], v[118:121], v[80:83], v[98:101]
	s_waitcnt lgkmcnt(6)
	v_mfma_f32_16x16x32_bf16 v[98:101], v[122:125], v[84:87], v[98:101]
	s_waitcnt lgkmcnt(5)
	v_mfma_f32_16x16x32_bf16 v[98:101], v[126:129], v[88:91], v[98:101]
	s_waitcnt lgkmcnt(4)
	v_mfma_f32_16x16x32_bf16 v[98:101], v[130:133], v[92:95], v[98:101]
	s_waitcnt lgkmcnt(0)
	v_mfma_f32_16x16x32_bf16 v[0:3], v[150:153], v[134:137], v[0:3]
	v_mfma_f32_16x16x32_bf16 v[16:19], v[154:157], v[134:137], v[16:19]
	v_mfma_f32_16x16x32_bf16 v[32:35], v[158:161], v[134:137], v[32:35]
	v_mfma_f32_16x16x32_bf16 v[48:51], v[162:165], v[134:137], v[48:51]
	v_mfma_f32_16x16x32_bf16 v[4:7], v[150:153], v[138:141], v[4:7]
	v_mfma_f32_16x16x32_bf16 v[20:23], v[154:157], v[138:141], v[20:23]
	v_mfma_f32_16x16x32_bf16 v[36:39], v[158:161], v[138:141], v[36:39]
	v_mfma_f32_16x16x32_bf16 v[52:55], v[162:165], v[138:141], v[52:55]
	v_mfma_f32_16x16x32_bf16 v[8:11], v[150:153], v[142:145], v[8:11]
	v_mfma_f32_16x16x32_bf16 v[24:27], v[154:157], v[142:145], v[24:27]
	v_mfma_f32_16x16x32_bf16 v[40:43], v[158:161], v[142:145], v[40:43]
	v_mfma_f32_16x16x32_bf16 v[56:59], v[162:165], v[142:145], v[56:59]
	v_mfma_f32_16x16x32_bf16 v[12:15], v[150:153], v[146:149], v[12:15]
	v_mfma_f32_16x16x32_bf16 v[28:31], v[154:157], v[146:149], v[28:31]
	v_mfma_f32_16x16x32_bf16 v[44:47], v[158:161], v[146:149], v[44:47]
	v_mfma_f32_16x16x32_bf16 v[60:63], v[162:165], v[146:149], v[60:63]
	v_mul_f32_e32 v170, v98, v166
	v_mul_f32_e32 v171, v99, v167
	v_mul_f32_e32 v172, v100, v168
	v_mul_f32_e32 v173, v101, v169
	v_cvt_pk_bf16_f32 v174, v170, v171
	v_cvt_pk_bf16_f32 v175, v172, v173
	ds_write_b64 v188, v[174:175] offset:0
	s_waitcnt vmcnt(6)
	ds_read_b64_tr_b16 v[150:151], v183 offset:0
	ds_read_b64_tr_b16 v[152:153], v183 offset:512
	ds_read_b64_tr_b16 v[154:155], v184 offset:0
	ds_read_b64_tr_b16 v[156:157], v184 offset:512
	ds_read_b64_tr_b16 v[158:159], v185 offset:0
	ds_read_b64_tr_b16 v[160:161], v185 offset:512
	ds_read_b64_tr_b16 v[162:163], v186 offset:0
	ds_read_b64_tr_b16 v[164:165], v186 offset:512
	s_waitcnt lgkmcnt(8)
	s_barrier
	s_add_i32 s27, s27, 1
	s_cmp_lt_u32 s27, 11
	s_cbranch_scc1 .Lret_loop
	s_cmp_lt_u32 s29, 32
	s_cbranch_scc0 .Lret_dctx_49
	s_mul_i32 s41, s29, 0xc0000
	s_mul_i32 s46, s31, 0x60000
	s_add_u32 s42, s78, s41
	s_addc_u32 s43, s79, 0
	s_add_u32 s42, s42, s46
	s_addc_u32 s43, s43, 0
	s_add_i32 m0, s54, 0
	s_nop 0
	global_load_lds_dwordx4 v189, s[42:43]
	s_add_i32 m0, s54, 1056
	s_nop 0
	global_load_lds_dwordx4 v190, s[42:43]
	s_branch .Lret_ddone_50

; #define RET_BAR() do { asm volatile("s_waitcnt lgkmcnt(0)" ::: "memory"); __builtin_amdgcn_s_barrier(); asm volatile("" ::: "memory"); } while (0)
; #define RET_LOADV(t) do { RET_KV(t) const char* vb_ = kb_ + (1024 + h * 256) * 2; const unsigned lo_ = (unsigned)(tid >> 6) * kp_ + (unsigned)(tid & 63) * 16u; \
;         _Pragma("unroll") for (int i_ = 0; i_ < 8; ++i_) vr[i_] = *(const u32x4*)(vb_ + (size_t)(8u * i_) * kp_ + lo_); } while (0)
; #define RET_STOREV() do { _Pragma("unroll") for (int i_ = 0; i_ < 8; ++i_) *(LAS u32x4*)(Vs + ((tid >> 6) + 8 * i_) * 1040 + (tid & 63) * 16) = vr[i_]; } while (0)
; __device__ __forceinline__ void ret_unit(ldsp lds, bf16_t* R, const bf16_t* RC, int b, int h, int qblk, float lgf2, float lgb2, const int tid_in) {
;     ...
;     f32x4 o[4][4];
; #pragma unroll
;     for (int db = 0; db < 4; ++db)
; #pragma unroll
;         for (int q4 = 0; q4 < 4; ++q4) o[db][q4] = (f32x4){0.f, 0.f, 0.f, 0.f};
;     ...
;     { const int tid = tid_outer, lane = tid & 63, l15 = lane & 15, lg = lane >> 4;
;       RET_BAR();
;       RET_DMAK(TI(0), 0); RET_DMAK(TI(1), 1); RET_LOADV(TI(0));
;       asm volatile("s_waitcnt vmcnt(0)" ::: "memory");
;       RET_STOREV();
;       RET_BAR();
;       RET_S(0, TI(0));
;       RET_LOADV(TI(1));
;       RET_BAR();
;       RET_DMAK(TI(2), 0); }
;     for (int t = 0; t < 36; ++t) {
;         int tl_ = tid_outer; asm volatile("" : "+v"(tl_));
;         const int tid = tl_, lane = tid & 63, l15 = lane & 15, lg = lane >> 4;
;         if (wid < 4) { RET_PV(t); if (t + 1 < 36) RET_S(t + 1, TI(t + 1)); }
;         else { if (t + 1 < 36) RET_S(t + 1, TI(t + 1)); RET_PV(t); }
;         RET_BAR();
;         asm volatile("s_waitcnt vmcnt(0)" ::: "memory");
;         if (t + 1 < 36) RET_STOREV();
;         if (t + 2 < 36) RET_LOADV(TI(t + 2));
;         if (t + 3 < 36) RET_DMAK(TI(t + 3), (t + 1) & 1);
;         RET_BAR();
;     }
.Lret_wdone_66:
	s_xor_b32 s38, s38, 1
	s_cmp_eq_u32 s38, 0
	s_cselect_b32 s41, 1, 0
	s_add_i32 s37, s37, s41
	s_cmp_eq_u32 s37, 36
	s_cselect_b32 s37, 0, s37
	s_waitcnt lgkmcnt(11)
	v_mfma_f32_16x16x32_bf16 v[98:101], v[102:105], v[64:67], 0
	s_waitcnt lgkmcnt(10)
	v_mfma_f32_16x16x32_bf16 v[98:101], v[106:109], v[68:71], v[98:101]
	s_waitcnt lgkmcnt(9)
	v_mfma_f32_16x16x32_bf16 v[98:101], v[110:113], v[72:75], v[98:101]
	s_waitcnt lgkmcnt(8)
	v_mfma_f32_16x16x32_bf16 v[98:101], v[114:117], v[76:79], v[98:101]
	s_waitcnt lgkmcnt(7)
	v_mfma_f32_16x16x32_bf16 v[98:101], v[118:121], v[80:83], v[98:101]
	s_waitcnt lgkmcnt(6)
	v_mfma_f32_16x16x32_bf16 v[98:101], v[122:125], v[84:87], v[98:101]
	s_waitcnt lgkmcnt(5)
	v_mfma_f32_16x16x32_bf16 v[98:101], v[126:129], v[88:91], v[98:101]
	s_waitcnt lgkmcnt(4)
	v_mfma_f32_16x16x32_bf16 v[98:101], v[130:133], v[92:95], v[98:101]
	s_waitcnt lgkmcnt(0)
	v_mfma_f32_16x16x32_bf16 v[0:3], v[150:153], v[134:137], v[0:3]
	v_mfma_f32_16x16x32_bf16 v[16:19], v[154:157], v[134:137], v[16:19]
	v_mfma_f32_16x16x32_bf16 v[32:35], v[158:161], v[134:137], v[32:35]
	v_mfma_f32_16x16x32_bf16 v[48:51], v[162:165], v[134:137], v[48:51]
	v_mfma_f32_16x16x32_bf16 v[4:7], v[150:153], v[138:141], v[4:7]
	v_mfma_f32_16x16x32_bf16 v[20:23], v[154:157], v[138:141], v[20:23]
	v_mfma_f32_16x16x32_bf16 v[36:39], v[158:161], v[138:141], v[36:39]
	v_mfma_f32_16x16x32_bf16 v[52:55], v[162:165], v[138:141], v[52:55]
	v_mfma_f32_16x16x32_bf16 v[8:11], v[150:153], v[142:145], v[8:11]
	v_mfma_f32_16x16x32_bf16 v[24:27], v[154:157], v[142:145], v[24:27]
	v_mfma_f32_16x16x32_bf16 v[40:43], v[158:161], v[142:145], v[40:43]
	v_mfma_f32_16x16x32_bf16 v[56:59], v[162:165], v[142:145], v[56:59]
	v_mfma_f32_16x16x32_bf16 v[12:15], v[150:153], v[146:149], v[12:15]
	v_mfma_f32_16x16x32_bf16 v[28:31], v[154:157], v[146:149], v[28:31]
	v_mfma_f32_16x16x32_bf16 v[44:47], v[158:161], v[146:149], v[44:47]
	v_mfma_f32_16x16x32_bf16 v[60:63], v[162:165], v[146:149], v[60:63]
	v_mul_f32_e32 v170, v98, v166
	v_mul_f32_e32 v171, v99, v167
	v_mul_f32_e32 v172, v100, v168
	v_mul_f32_e32 v173, v101, v169
	v_cvt_pk_bf16_f32 v174, v170, v171
	v_cvt_pk_bf16_f32 v175, v172, v173
	ds_write_b64 v188, v[174:175] offset:5120
	s_waitcnt vmcnt(6)
	ds_read_b64_tr_b16 v[150:151], v183 offset:0
	ds_read_b64_tr_b16 v[152:153], v183 offset:512
	ds_read_b64_tr_b16 v[154:155], v184 offset:0
	ds_read_b64_tr_b16 v[156:157], v184 offset:512
	ds_read_b64_tr_b16 v[158:159], v185 offset:0
	ds_read_b64_tr_b16 v[160:161], v185 offset:512
	ds_read_b64_tr_b16 v[162:163], v186 offset:0
	ds_read_b64_tr_b16 v[164:165], v186 offset:512
	s_waitcnt lgkmcnt(8)
	s_barrier
	s_cmp_lt_u32 s34, 32
	s_cbranch_scc0 .Lret_dctx_67
	s_mul_i32 s41, s34, 0xc0000
	s_mul_i32 s46, s36, 0x60000
	s_add_u32 s44, s78, s41
	s_addc_u32 s45, s79, 0
	s_add_u32 s44, s44, s46
	s_addc_u32 s45, s45, 0
	s_add_i32 m0, s55, 8192
	s_nop 0
	global_load_lds_dwordx4 v193, s[44:45]
	s_add_i32 m0, s55, 9216
	s_nop 0
	global_load_lds_dwordx4 v194, s[44:45]
	s_add_i32 m0, s55, 10240
	s_nop 0
	global_load_lds_dwordx4 v195, s[44:45]
	s_add_i32 m0, s55, 11264
	s_nop 0
	global_load_lds_dwordx4 v197, s[44:45]
	s_branch .Lret_ddone_68

; #define RET_BAR() do { asm volatile("s_waitcnt lgkmcnt(0)" ::: "memory"); __builtin_amdgcn_s_barrier(); asm volatile("" ::: "memory"); } while (0)
; #define RET_LOADV(t) do { RET_KV(t) const char* vb_ = kb_ + (1024 + h * 256) * 2; const unsigned lo_ = (unsigned)(tid >> 6) * kp_ + (unsigned)(tid & 63) * 16u; \
;         _Pragma("unroll") for (int i_ = 0; i_ < 8; ++i_) vr[i_] = *(const u32x4*)(vb_ + (size_t)(8u * i_) * kp_ + lo_); } while (0)
; #define RET_STOREV() do { _Pragma("unroll") for (int i_ = 0; i_ < 8; ++i_) *(LAS u32x4*)(Vs + ((tid >> 6) + 8 * i_) * 1040 + (tid & 63) * 16) = vr[i_]; } while (0)
; __device__ __forceinline__ void ret_unit(ldsp lds, bf16_t* R, const bf16_t* RC, int b, int h, int qblk, float lgf2, float lgb2, const int tid_in) {
;     ...
;     f32x4 o[4][4];
; #pragma unroll
;     for (int db = 0; db < 4; ++db)
; #pragma unroll
;         for (int q4 = 0; q4 < 4; ++q4) o[db][q4] = (f32x4){0.f, 0.f, 0.f, 0.f};
;     ...
;     { const int tid = tid_outer, lane = tid & 63, l15 = lane & 15, lg = lane >> 4;
;       RET_BAR();
;       RET_DMAK(TI(0), 0); RET_DMAK(TI(1), 1); RET_LOADV(TI(0));
;       asm volatile("s_waitcnt vmcnt(0)" ::: "memory");
;       RET_STOREV();
;       RET_BAR();
;       RET_S(0, TI(0));
;       RET_LOADV(TI(1));
;       RET_BAR();
;       RET_DMAK(TI(2), 0); }
;     for (int t = 0; t < 36; ++t) {
;         int tl_ = tid_outer; asm volatile("" : "+v"(tl_));
;         const int tid = tl_, lane = tid & 63, l15 = lane & 15, lg = lane >> 4;
;         if (wid < 4) { RET_PV(t); if (t + 1 < 36) RET_S(t + 1, TI(t + 1)); }
;         else { if (t + 1 < 36) RET_S(t + 1, TI(t + 1)); RET_PV(t); }
;         RET_BAR();
;         asm volatile("s_waitcnt vmcnt(0)" ::: "memory");
;         if (t + 1 < 36) RET_STOREV();
;         if (t + 2 < 36) RET_LOADV(TI(t + 2));
;         if (t + 3 < 36) RET_DMAK(TI(t + 3), (t + 1) & 1);
;         RET_BAR();
;     }
.Lret_wdone_70:
	s_xor_b32 s38, s38, 1
	s_cmp_eq_u32 s38, 0
	s_cselect_b32 s41, 1, 0
	s_add_i32 s37, s37, s41
	s_cmp_eq_u32 s37, 36
	s_cselect_b32 s37, 0, s37
	s_waitcnt lgkmcnt(11)
	v_mfma_f32_16x16x32_bf16 v[98:101], v[102:105], v[64:67], 0
	s_waitcnt lgkmcnt(10)
	v_mfma_f32_16x16x32_bf16 v[98:101], v[106:109], v[68:71], v[98:101]
	s_waitcnt lgkmcnt(9)
	v_mfma_f32_16x16x32_bf16 v[98:101], v[110:113], v[72:75], v[98:101]
	s_waitcnt lgkmcnt(8)
	v_mfma_f32_16x16x32_bf16 v[98:101], v[114:117], v[76:79], v[98:101]
	s_waitcnt lgkmcnt(7)
	v_mfma_f32_16x16x32_bf16 v[98:101], v[118:121], v[80:83], v[98:101]
	s_waitcnt lgkmcnt(6)
	v_mfma_f32_16x16x32_bf16 v[98:101], v[122:125], v[84:87], v[98:101]
	s_waitcnt lgkmcnt(5)
	v_mfma_f32_16x16x32_bf16 v[98:101], v[126:129], v[88:91], v[98:101]
	s_waitcnt lgkmcnt(4)
	v_mfma_f32_16x16x32_bf16 v[98:101], v[130:133], v[92:95], v[98:101]
	s_waitcnt lgkmcnt(0)
	v_mfma_f32_16x16x32_bf16 v[0:3], v[150:153], v[134:137], v[0:3]
	v_mfma_f32_16x16x32_bf16 v[16:19], v[154:157], v[134:137], v[16:19]
	v_mfma_f32_16x16x32_bf16 v[32:35], v[158:161], v[134:137], v[32:35]
	v_mfma_f32_16x16x32_bf16 v[48:51], v[162:165], v[134:137], v[48:51]
	v_mfma_f32_16x16x32_bf16 v[4:7], v[150:153], v[138:141], v[4:7]
	v_mfma_f32_16x16x32_bf16 v[20:23], v[154:157], v[138:141], v[20:23]
	v_mfma_f32_16x16x32_bf16 v[36:39], v[158:161], v[138:141], v[36:39]
	v_mfma_f32_16x16x32_bf16 v[52:55], v[162:165], v[138:141], v[52:55]
	v_mfma_f32_16x16x32_bf16 v[8:11], v[150:153], v[142:145], v[8:11]
	v_mfma_f32_16x16x32_bf16 v[24:27], v[154:157], v[142:145], v[24:27]
	v_mfma_f32_16x16x32_bf16 v[40:43], v[158:161], v[142:145], v[40:43]
	v_mfma_f32_16x16x32_bf16 v[56:59], v[162:165], v[142:145], v[56:59]
	v_mfma_f32_16x16x32_bf16 v[12:15], v[150:153], v[146:149], v[12:15]
	v_mfma_f32_16x16x32_bf16 v[28:31], v[154:157], v[146:149], v[28:31]
	v_mfma_f32_16x16x32_bf16 v[44:47], v[158:161], v[146:149], v[44:47]
	v_mfma_f32_16x16x32_bf16 v[60:63], v[162:165], v[146:149], v[60:63]
	v_mul_f32_e32 v170, v98, v166
	v_mul_f32_e32 v171, v99, v167
	v_mul_f32_e32 v172, v100, v168
	v_mul_f32_e32 v173, v101, v169
	v_cvt_pk_bf16_f32 v174, v170, v171
	v_cvt_pk_bf16_f32 v175, v172, v173
	ds_write_b64 v188, v[174:175] offset:0
	s_waitcnt vmcnt(4)
	ds_read_b64_tr_b16 v[150:151], v183 offset:4096
	ds_read_b64_tr_b16 v[152:153], v183 offset:4608
	ds_read_b64_tr_b16 v[154:155], v184 offset:4096
	ds_read_b64_tr_b16 v[156:157], v184 offset:4608
	ds_read_b64_tr_b16 v[158:159], v185 offset:4096
	ds_read_b64_tr_b16 v[160:161], v185 offset:4608
	ds_read_b64_tr_b16 v[162:163], v186 offset:4096
	ds_read_b64_tr_b16 v[164:165], v186 offset:4608
	s_waitcnt lgkmcnt(8)
	s_barrier
	ds_read_b128 v[102:105], v182 offset:33792
	ds_read_b128 v[106:109], v182 offset:33856
	ds_read_b128 v[110:113], v182 offset:33920
	ds_read_b128 v[114:117], v182 offset:33984
	ds_read_b128 v[118:121], v182 offset:34048
	ds_read_b128 v[122:125], v182 offset:34112
	ds_read_b128 v[126:129], v182 offset:34176
	ds_read_b128 v[130:133], v182 offset:34240
	ds_read_b128 v[134:137], v187 offset:0
	ds_read_b128 v[138:141], v187 offset:1280
	ds_read_b128 v[142:145], v187 offset:2560
	ds_read_b128 v[146:149], v187 offset:3840
	s_cmp_lt_u32 s37, 32
	s_cbranch_scc0 .Lret_wctx_71
	s_lshl_b32 s100, s37, 6
	s_lshl_b32 s41, s38, 5
	s_add_i32 s100, s100, s41
	v_subrev_u32_e32 v170, s100, v203
	v_subrev_u32_e32 v171, s100, v204
	v_subrev_u32_e32 v172, s100, v205
	v_subrev_u32_e32 v173, s100, v206
	v_cvt_f32_i32_e32 v174, v170
	v_cvt_f32_i32_e32 v175, v171
	v_cvt_f32_i32_e32 v176, v172
	v_cvt_f32_i32_e32 v177, v173
	v_cmp_gt_i32_e32 vcc, 0, v170
	s_nop 1
	v_cndmask_b32_e32 v178, v207, v208, vcc
	v_cmp_gt_i32_e32 vcc, 0, v171
	s_nop 1
	v_cndmask_b32_e32 v179, v207, v208, vcc
	v_cmp_gt_i32_e32 vcc, 0, v172
	s_nop 1
	v_cndmask_b32_e32 v180, v207, v208, vcc
	v_cmp_gt_i32_e32 vcc, 0, v173
	s_nop 1
	v_cndmask_b32_e32 v181, v207, v208, vcc
	v_mul_f32_e64 v178, v178, |v174|
	v_mul_f32_e64 v179, v179, |v175|
	v_mul_f32_e64 v180, v180, |v176|
	v_mul_f32_e64 v181, v181, |v177|
	v_exp_f32_e32 v166, v178
	v_exp_f32_e32 v167, v179
	v_exp_f32_e32 v168, v180
	v_exp_f32_e32 v169, v181
	s_branch .Lret_wdone_72

; #define LAS __attribute__((address_space(3)))
; #define RET_BAR() do { asm volatile("s_waitcnt lgkmcnt(0)" ::: "memory"); __builtin_amdgcn_s_barrier(); asm volatile("" ::: "memory"); } while (0)
; __device__ __forceinline__ void ret_unit(ldsp lds, bf16_t* R, const bf16_t* RC, int b, int h, int qblk, float lgf2, float lgb2, const int tid_in) {
;     ...
;     const int lane = tid_outer & 63, l15 = lane & 15, lg = lane >> 4;
;     LAS float* red = (LAS float*)Ps;
; #pragma unroll
;     for (int q4 = 0; q4 < 4; ++q4) {
;         float ss = 0.f;
; #pragma unroll
;         for (int db = 0; db < 4; ++db)
; #pragma unroll
;             for (int j = 0; j < 4; ++j) ss += o[db][q4][j] * o[db][q4][j];
;         ss += __shfl_xor(ss, 16); ss += __shfl_xor(ss, 32);
;         if (lg == 0) red[wid * 64 + 16 * q4 + l15] = ss;
;     }
;     RET_BAR();
.Lret_wdone_72:
	s_xor_b32 s38, s38, 1
	s_cmp_eq_u32 s38, 0
	s_cselect_b32 s41, 1, 0
	s_add_i32 s37, s37, s41
	s_cmp_eq_u32 s37, 36
	s_cselect_b32 s37, 0, s37
	s_waitcnt lgkmcnt(11)
	v_mfma_f32_16x16x32_bf16 v[98:101], v[102:105], v[64:67], 0
	s_waitcnt lgkmcnt(10)
	v_mfma_f32_16x16x32_bf16 v[98:101], v[106:109], v[68:71], v[98:101]
	s_waitcnt lgkmcnt(9)
	v_mfma_f32_16x16x32_bf16 v[98:101], v[110:113], v[72:75], v[98:101]
	s_waitcnt lgkmcnt(8)
	v_mfma_f32_16x16x32_bf16 v[98:101], v[114:117], v[76:79], v[98:101]
	s_waitcnt lgkmcnt(7)
	v_mfma_f32_16x16x32_bf16 v[98:101], v[118:121], v[80:83], v[98:101]
	s_waitcnt lgkmcnt(6)
	v_mfma_f32_16x16x32_bf16 v[98:101], v[122:125], v[84:87], v[98:101]
	s_waitcnt lgkmcnt(5)
	v_mfma_f32_16x16x32_bf16 v[98:101], v[126:129], v[88:91], v[98:101]
	s_waitcnt lgkmcnt(4)
	v_mfma_f32_16x16x32_bf16 v[98:101], v[130:133], v[92:95], v[98:101]
	s_waitcnt lgkmcnt(0)
	v_mfma_f32_16x16x32_bf16 v[0:3], v[150:153], v[134:137], v[0:3]
	v_mfma_f32_16x16x32_bf16 v[16:19], v[154:157], v[134:137], v[16:19]
	v_mfma_f32_16x16x32_bf16 v[32:35], v[158:161], v[134:137], v[32:35]
	v_mfma_f32_16x16x32_bf16 v[48:51], v[162:165], v[134:137], v[48:51]
	v_mfma_f32_16x16x32_bf16 v[4:7], v[150:153], v[138:141], v[4:7]
	v_mfma_f32_16x16x32_bf16 v[20:23], v[154:157], v[138:141], v[20:23]
	v_mfma_f32_16x16x32_bf16 v[36:39], v[158:161], v[138:141], v[36:39]
	v_mfma_f32_16x16x32_bf16 v[52:55], v[162:165], v[138:141], v[52:55]
	v_mfma_f32_16x16x32_bf16 v[8:11], v[150:153], v[142:145], v[8:11]
	v_mfma_f32_16x16x32_bf16 v[24:27], v[154:157], v[142:145], v[24:27]
	v_mfma_f32_16x16x32_bf16 v[40:43], v[158:161], v[142:145], v[40:43]
	v_mfma_f32_16x16x32_bf16 v[56:59], v[162:165], v[142:145], v[56:59]
	v_mfma_f32_16x16x32_bf16 v[12:15], v[150:153], v[146:149], v[12:15]
	v_mfma_f32_16x16x32_bf16 v[28:31], v[154:157], v[146:149], v[28:31]
	v_mfma_f32_16x16x32_bf16 v[44:47], v[158:161], v[146:149], v[44:47]
	v_mfma_f32_16x16x32_bf16 v[60:63], v[162:165], v[146:149], v[60:63]
	v_mul_f32_e32 v170, v98, v166
	v_mul_f32_e32 v171, v99, v167
	v_mul_f32_e32 v172, v100, v168
	v_mul_f32_e32 v173, v101, v169
	v_cvt_pk_bf16_f32 v174, v170, v171
	v_cvt_pk_bf16_f32 v175, v172, v173
	ds_write_b64 v188, v[174:175] offset:5120
	s_waitcnt vmcnt(0)
	ds_read_b64_tr_b16 v[150:151], v183 offset:8192
	ds_read_b64_tr_b16 v[152:153], v183 offset:8704
	ds_read_b64_tr_b16 v[154:155], v184 offset:8192
	ds_read_b64_tr_b16 v[156:157], v184 offset:8704
	ds_read_b64_tr_b16 v[158:159], v185 offset:8192
	ds_read_b64_tr_b16 v[160:161], v185 offset:8704
	ds_read_b64_tr_b16 v[162:163], v186 offset:8192
	ds_read_b64_tr_b16 v[164:165], v186 offset:8704
	s_waitcnt lgkmcnt(8)
	s_barrier
	ds_read_b128 v[134:137], v187 offset:5120
	ds_read_b128 v[138:141], v187 offset:6400
	ds_read_b128 v[142:145], v187 offset:7680
	ds_read_b128 v[146:149], v187 offset:8960
	s_waitcnt lgkmcnt(0)
	v_mfma_f32_16x16x32_bf16 v[0:3], v[150:153], v[134:137], v[0:3]
	v_mfma_f32_16x16x32_bf16 v[16:19], v[154:157], v[134:137], v[16:19]
	v_mfma_f32_16x16x32_bf16 v[32:35], v[158:161], v[134:137], v[32:35]
	v_mfma_f32_16x16x32_bf16 v[48:51], v[162:165], v[134:137], v[48:51]
	v_mfma_f32_16x16x32_bf16 v[4:7], v[150:153], v[138:141], v[4:7]
	v_mfma_f32_16x16x32_bf16 v[20:23], v[154:157], v[138:141], v[20:23]
	v_mfma_f32_16x16x32_bf16 v[36:39], v[158:161], v[138:141], v[36:39]
	v_mfma_f32_16x16x32_bf16 v[52:55], v[162:165], v[138:141], v[52:55]
	v_mfma_f32_16x16x32_bf16 v[8:11], v[150:153], v[142:145], v[8:11]
	v_mfma_f32_16x16x32_bf16 v[24:27], v[154:157], v[142:145], v[24:27]
	v_mfma_f32_16x16x32_bf16 v[40:43], v[158:161], v[142:145], v[40:43]
	v_mfma_f32_16x16x32_bf16 v[56:59], v[162:165], v[142:145], v[56:59]
	v_mfma_f32_16x16x32_bf16 v[12:15], v[150:153], v[146:149], v[12:15]
	v_mfma_f32_16x16x32_bf16 v[28:31], v[154:157], v[146:149], v[28:31]
	v_mfma_f32_16x16x32_bf16 v[44:47], v[158:161], v[146:149], v[44:47]
	v_mfma_f32_16x16x32_bf16 v[60:63], v[162:165], v[146:149], v[60:63]
	s_waitcnt lgkmcnt(0)
	s_barrier
	s_lshl_b32 s46, s7, 10
	s_mul_i32 s41, s13, 0x3000
	s_add_u32 s86, s22, s41
	s_addc_u32 s87, s23, 0
	s_add_u32 s86, s86, s46
	s_addc_u32 s87, s87, 0
	s_add_u32 s86, s86, 0x2000
	s_addc_u32 s87, s87, 0
	global_load_dwordx2 v[102:103], v226, s[86:87] offset:0
	global_load_dwordx2 v[104:105], v226, s[86:87] offset:32
	global_load_dwordx2 v[106:107], v226, s[86:87] offset:64
	global_load_dwordx2 v[108:109], v226, s[86:87] offset:96
	global_load_dwordx2 v[110:111], v227, s[86:87] offset:0
	global_load_dwordx2 v[112:113], v227, s[86:87] offset:32
	global_load_dwordx2 v[114:115], v227, s[86:87] offset:64
	global_load_dwordx2 v[116:117], v227, s[86:87] offset:96
	global_load_dwordx2 v[118:119], v228, s[86:87] offset:0
	global_load_dwordx2 v[120:121], v228, s[86:87] offset:32
	global_load_dwordx2 v[122:123], v228, s[86:87] offset:64
	global_load_dwordx2 v[124:125], v228, s[86:87] offset:96
	global_load_dwordx2 v[126:127], v229, s[86:87] offset:0
	global_load_dwordx2 v[128:129], v229, s[86:87] offset:32
	global_load_dwordx2 v[130:131], v229, s[86:87] offset:64
	global_load_dwordx2 v[132:133], v229, s[86:87] offset:96
	v_xor_b32_e32 v212, 16, v211
	v_lshlrev_b32_e32 v212, 2, v212
	v_xor_b32_e32 v213, 32, v211
	v_lshlrev_b32_e32 v213, 2, v213
	s_lshl_b32 s46, s10, 8
	v_lshl_add_u32 v214, v209, 2, s46
	v_cmp_gt_u32_e64 s[4:5], 16, v211
	v_mul_f32_e32 v230, v1, v1
	v_fmac_f32_e32 v230, v0, v0
	v_fmac_f32_e32 v230, v2, v2
	v_fmac_f32_e32 v230, v3, v3
	v_fmac_f32_e32 v230, v16, v16
	v_fmac_f32_e32 v230, v17, v17
	v_fmac_f32_e32 v230, v18, v18
	v_fmac_f32_e32 v230, v19, v19
	v_fmac_f32_e32 v230, v32, v32
	v_fmac_f32_e32 v230, v33, v33
; #define LAS __attribute__((address_space(3)))
; #define RET_BAR() do { asm volatile("s_waitcnt lgkmcnt(0)" ::: "memory"); __builtin_amdgcn_s_barrier(); asm volatile("" ::: "memory"); } while (0)
; __device__ __forceinline__ void ret_unit(ldsp lds, bf16_t* R, const bf16_t* RC, int b, int h, int qblk, float lgf2, float lgb2, const int tid_in) {
;     ...
;     const int lane = tid_outer & 63, l15 = lane & 15, lg = lane >> 4;
;     LAS float* red = (LAS float*)Ps;
; #pragma unroll
;     for (int q4 = 0; q4 < 4; ++q4) {
;         float ss = 0.f;
; #pragma unroll
;         for (int db = 0; db < 4; ++db)
; #pragma unroll
;             for (int j = 0; j < 4; ++j) ss += o[db][q4][j] * o[db][q4][j];
;         ss += __shfl_xor(ss, 16); ss += __shfl_xor(ss, 32);
;         if (lg == 0) red[wid * 64 + 16 * q4 + l15] = ss;
;     }
;     RET_BAR();
; #pragma unroll
;     for (int q4 = 0; q4 < 4; ++q4) {
;         float tot = 0.f;
; #pragma unroll
;         for (int w = 0; w < 8; ++w) tot += red[w * 64 + 16 * q4 + l15];
;         const float rstd = 1.0f / sqrtf(tot * (1.f / 512.f) + EPS);
	v_fmac_f32_e32 v230, v34, v34
	v_fmac_f32_e32 v230, v35, v35
	v_fmac_f32_e32 v230, v48, v48
	v_fmac_f32_e32 v230, v49, v49
	v_fmac_f32_e32 v230, v50, v50
	v_fmac_f32_e32 v230, v51, v51
	v_mul_f32_e32 v231, v5, v5
	v_fmac_f32_e32 v231, v4, v4
	v_fmac_f32_e32 v231, v6, v6
	v_fmac_f32_e32 v231, v7, v7
	v_fmac_f32_e32 v231, v20, v20
	v_fmac_f32_e32 v231, v21, v21
	v_fmac_f32_e32 v231, v22, v22
	v_fmac_f32_e32 v231, v23, v23
	v_fmac_f32_e32 v231, v36, v36
	v_fmac_f32_e32 v231, v37, v37
	v_fmac_f32_e32 v231, v38, v38
	v_fmac_f32_e32 v231, v39, v39
	v_fmac_f32_e32 v231, v52, v52
	v_fmac_f32_e32 v231, v53, v53
	v_fmac_f32_e32 v231, v54, v54
	v_fmac_f32_e32 v231, v55, v55
	v_mul_f32_e32 v232, v9, v9
	v_fmac_f32_e32 v232, v8, v8
	v_fmac_f32_e32 v232, v10, v10
	v_fmac_f32_e32 v232, v11, v11
	v_fmac_f32_e32 v232, v24, v24
	v_fmac_f32_e32 v232, v25, v25
	v_fmac_f32_e32 v232, v26, v26
	v_fmac_f32_e32 v232, v27, v27
	v_fmac_f32_e32 v232, v40, v40
	v_fmac_f32_e32 v232, v41, v41
	v_fmac_f32_e32 v232, v42, v42
	v_fmac_f32_e32 v232, v43, v43
	v_fmac_f32_e32 v232, v56, v56
	v_fmac_f32_e32 v232, v57, v57
	v_fmac_f32_e32 v232, v58, v58
	v_fmac_f32_e32 v232, v59, v59
	v_mul_f32_e32 v233, v13, v13
	v_fmac_f32_e32 v233, v12, v12
	v_fmac_f32_e32 v233, v14, v14
	v_fmac_f32_e32 v233, v15, v15
	v_fmac_f32_e32 v233, v28, v28
	v_fmac_f32_e32 v233, v29, v29
	v_fmac_f32_e32 v233, v30, v30
	v_fmac_f32_e32 v233, v31, v31
	v_fmac_f32_e32 v233, v44, v44
	v_fmac_f32_e32 v233, v45, v45
	v_fmac_f32_e32 v233, v46, v46
	v_fmac_f32_e32 v233, v47, v47
	v_fmac_f32_e32 v233, v60, v60
	v_fmac_f32_e32 v233, v61, v61
	v_fmac_f32_e32 v233, v62, v62
	v_fmac_f32_e32 v233, v63, v63
	ds_bpermute_b32 v234, v212, v230
	ds_bpermute_b32 v235, v212, v231
	ds_bpermute_b32 v236, v212, v232
	ds_bpermute_b32 v237, v212, v233
	s_waitcnt lgkmcnt(0)
	v_add_f32_e32 v230, v230, v234
	v_add_f32_e32 v231, v231, v235
	v_add_f32_e32 v232, v232, v236
	v_add_f32_e32 v233, v233, v237
	ds_bpermute_b32 v234, v213, v230
	ds_bpermute_b32 v235, v213, v231
	ds_bpermute_b32 v236, v213, v232
	ds_bpermute_b32 v237, v213, v233
	s_waitcnt lgkmcnt(0)
	v_add_f32_e32 v230, v230, v234
	v_add_f32_e32 v231, v231, v235
	v_add_f32_e32 v232, v232, v236
	v_add_f32_e32 v233, v233, v237
	s_mov_b64 s[42:43], exec
	s_and_b64 exec, exec, s[4:5]
	ds_write_b32 v214, v230 offset:0
	ds_write_b32 v214, v231 offset:64
	ds_write_b32 v214, v232 offset:128
	ds_write_b32 v214, v233 offset:192
	s_mov_b64 exec, s[42:43]
	s_waitcnt lgkmcnt(0)
	s_barrier
	v_lshlrev_b32_e32 v214, 2, v209
	ds_read_b32 v134, v214 offset:0
	ds_read_b32 v135, v214 offset:256
	ds_read_b32 v136, v214 offset:512
	ds_read_b32 v137, v214 offset:768
	ds_read_b32 v138, v214 offset:1024
	ds_read_b32 v139, v214 offset:1280
	ds_read_b32 v140, v214 offset:1536
	ds_read_b32 v141, v214 offset:1792
	ds_read_b32 v142, v214 offset:64
	ds_read_b32 v143, v214 offset:320
	ds_read_b32 v144, v214 offset:576
	ds_read_b32 v145, v214 offset:832
	ds_read_b32 v146, v214 offset:1088
	ds_read_b32 v147, v214 offset:1344
	ds_read_b32 v148, v214 offset:1600
	ds_read_b32 v149, v214 offset:1856
	ds_read_b32 v150, v214 offset:128
	ds_read_b32 v151, v214 offset:384
	ds_read_b32 v152, v214 offset:640
	ds_read_b32 v153, v214 offset:896
	ds_read_b32 v154, v214 offset:1152
	ds_read_b32 v155, v214 offset:1408
	ds_read_b32 v156, v214 offset:1664
	ds_read_b32 v157, v214 offset:1920
	ds_read_b32 v158, v214 offset:192
	ds_read_b32 v159, v214 offset:448
	ds_read_b32 v160, v214 offset:704
	ds_read_b32 v161, v214 offset:960
	ds_read_b32 v162, v214 offset:1216
	ds_read_b32 v163, v214 offset:1472
	ds_read_b32 v164, v214 offset:1728
	ds_read_b32 v165, v214 offset:1984
	s_waitcnt lgkmcnt(0)
	v_add_f32_e32 v230, 0, v134
	v_add_f32_e32 v230, v230, v135
	v_add_f32_e32 v230, v230, v136
	v_add_f32_e32 v230, v230, v137
	v_add_f32_e32 v230, v230, v138
	v_add_f32_e32 v230, v230, v139
	v_add_f32_e32 v230, v230, v140
	v_add_f32_e32 v230, v230, v141
	v_fmamk_f32 v230, v230, 0x3b000000, v221
	v_cmp_gt_f32_e32 vcc, s83, v230
	v_mul_f32_e32 v238, 0x4f800000, v230
	s_nop 0
	v_cndmask_b32_e32 v230, v230, v238, vcc
	v_sqrt_f32_e32 v238, v230
	s_nop 0
	v_add_u32_e32 v239, -1, v238
	v_fma_f32 v240, -v239, v238, v230
	v_cmp_ge_f32_e64 s[4:5], 0, v240
	v_add_u32_e32 v240, 1, v238
	s_nop 0
	v_cndmask_b32_e64 v239, v238, v239, s[4:5]
	v_fma_f32 v238, -v240, v238, v230
	v_cmp_lt_f32_e64 s[4:5], 0, v238
	s_nop 1
	v_cndmask_b32_e64 v238, v239, v240, s[4:5]
	v_mul_f32_e32 v239, 0x37800000, v238
	v_cndmask_b32_e32 v238, v238, v239, vcc
	v_cmp_class_f32_e32 vcc, v230, v222
	s_nop 1
	v_cndmask_b32_e32 v230, v238, v230, vcc
	v_div_scale_f32 v238, s[4:5], v230, v230, 1.0
	v_rcp_f32_e32 v239, v238
	s_nop 0
	v_fma_f32 v240, -v238, v239, 1.0
	v_fmac_f32_e32 v239, v240, v239
	v_div_scale_f32 v240, vcc, 1.0, v230, 1.0
	v_mul_f32_e32 v241, v240, v239
	v_fma_f32 v242, -v238, v241, v240
	v_fmac_f32_e32 v241, v242, v239
	v_fma_f32 v238, -v238, v241, v240
	s_nop 1
	v_div_fmas_f32 v238, v238, v239, v241
	v_div_fixup_f32 v250, v238, v230, 1.0
	v_add_f32_e32 v231, 0, v142
	v_add_f32_e32 v231, v231, v143
	v_add_f32_e32 v231, v231, v144
	v_add_f32_e32 v231, v231, v145
	v_add_f32_e32 v231, v231, v146
	v_add_f32_e32 v231, v231, v147
	v_add_f32_e32 v231, v231, v148
	v_add_f32_e32 v231, v231, v149
	v_fmamk_f32 v231, v231, 0x3b000000, v221
	v_cmp_gt_f32_e32 vcc, s83, v231
	v_mul_f32_e32 v238, 0x4f800000, v231
	s_nop 0
	v_cndmask_b32_e32 v231, v231, v238, vcc
	v_sqrt_f32_e32 v238, v231
	s_nop 0
	v_add_u32_e32 v239, -1, v238
	v_fma_f32 v240, -v239, v238, v231
	v_cmp_ge_f32_e64 s[4:5], 0, v240
	v_add_u32_e32 v240, 1, v238
	s_nop 0
	v_cndmask_b32_e64 v239, v238, v239, s[4:5]
; __device__ __forceinline__ unsigned cvt_pk_bf16(float lo, float hi) { unsigned r; asm volatile("v_cvt_pk_bf16_f32 %0, %1, %2" : "=v"(r) : "v"(lo), "v"(hi)); return r; }
; __device__ __forceinline__ float bflo(unsigned w) { return __uint_as_float(w << 16); }
; __device__ __forceinline__ float bfhi(unsigned w) { return __uint_as_float(w & 0xffff0000u); }
; __device__ __forceinline__ float silu_f(float x) { return x * __builtin_amdgcn_rcpf(1.0f + __builtin_amdgcn_exp2f(x * -1.4426950408889634f)); }
; __device__ __forceinline__ void ret_unit(ldsp lds, bf16_t* R, const bf16_t* RC, int b, int h, int qblk, float lgf2, float lgb2, const int tid_in) {
;     ...
;     for (int q4 = 0; q4 < 4; ++q4) {
;         float tot = 0.f;
; #pragma unroll
;         for (int w = 0; w < 8; ++w) tot += red[w * 64 + 16 * q4 + l15];
;         const float rstd = 1.0f / sqrtf(tot * (1.f / 512.f) + EPS);
;         bf16_t* gp = R + (size_t)(rowq0 + 16 * q4 + l15) * 6144 + 4096 + h * 512 + 64 * wid + 4 * lg;
; #pragma unroll
;         for (int db = 0; db < 4; ++db) { const u32x2 g2 = *(const u32x2*)(gp + 16 * db);
;             u32x2 w; w.x = cvt_pk_bf16(o[db][q4][0] * rstd * silu_f(bflo(g2.x)), o[db][q4][1] * rstd * silu_f(bfhi(g2.x)));
;             w.y = cvt_pk_bf16(o[db][q4][2] * rstd * silu_f(bflo(g2.y)), o[db][q4][3] * rstd * silu_f(bfhi(g2.y)));
;             *(u32x2*)(gp + 16 * db) = w; }
;     }
	v_fma_f32 v238, -v240, v238, v231
	v_cmp_lt_f32_e64 s[4:5], 0, v238
	s_nop 1
	v_cndmask_b32_e64 v238, v239, v240, s[4:5]
	v_mul_f32_e32 v239, 0x37800000, v238
	v_cndmask_b32_e32 v238, v238, v239, vcc
	v_cmp_class_f32_e32 vcc, v231, v222
	s_nop 1
	v_cndmask_b32_e32 v231, v238, v231, vcc
	v_div_scale_f32 v238, s[4:5], v231, v231, 1.0
	v_rcp_f32_e32 v239, v238
	s_nop 0
	v_fma_f32 v240, -v238, v239, 1.0
	v_fmac_f32_e32 v239, v240, v239
	v_div_scale_f32 v240, vcc, 1.0, v231, 1.0
	v_mul_f32_e32 v241, v240, v239
	v_fma_f32 v242, -v238, v241, v240
	v_fmac_f32_e32 v241, v242, v239
	v_fma_f32 v238, -v238, v241, v240
	s_nop 1
	v_div_fmas_f32 v238, v238, v239, v241
	v_div_fixup_f32 v251, v238, v231, 1.0
	v_add_f32_e32 v232, 0, v150
	v_add_f32_e32 v232, v232, v151
	v_add_f32_e32 v232, v232, v152
	v_add_f32_e32 v232, v232, v153
	v_add_f32_e32 v232, v232, v154
	v_add_f32_e32 v232, v232, v155
	v_add_f32_e32 v232, v232, v156
	v_add_f32_e32 v232, v232, v157
	v_fmamk_f32 v232, v232, 0x3b000000, v221
	v_cmp_gt_f32_e32 vcc, s83, v232
	v_mul_f32_e32 v238, 0x4f800000, v232
	s_nop 0
	v_cndmask_b32_e32 v232, v232, v238, vcc
	v_sqrt_f32_e32 v238, v232
	s_nop 0
	v_add_u32_e32 v239, -1, v238
	v_fma_f32 v240, -v239, v238, v232
	v_cmp_ge_f32_e64 s[4:5], 0, v240
	v_add_u32_e32 v240, 1, v238
	s_nop 0
	v_cndmask_b32_e64 v239, v238, v239, s[4:5]
	v_fma_f32 v238, -v240, v238, v232
	v_cmp_lt_f32_e64 s[4:5], 0, v238
	s_nop 1
	v_cndmask_b32_e64 v238, v239, v240, s[4:5]
	v_mul_f32_e32 v239, 0x37800000, v238
	v_cndmask_b32_e32 v238, v238, v239, vcc
	v_cmp_class_f32_e32 vcc, v232, v222
	s_nop 1
	v_cndmask_b32_e32 v232, v238, v232, vcc
	v_div_scale_f32 v238, s[4:5], v232, v232, 1.0
	v_rcp_f32_e32 v239, v238
	s_nop 0
	v_fma_f32 v240, -v238, v239, 1.0
	v_fmac_f32_e32 v239, v240, v239
	v_div_scale_f32 v240, vcc, 1.0, v232, 1.0
	v_mul_f32_e32 v241, v240, v239
	v_fma_f32 v242, -v238, v241, v240
	v_fmac_f32_e32 v241, v242, v239
	v_fma_f32 v238, -v238, v241, v240
	s_nop 1
	v_div_fmas_f32 v238, v238, v239, v241
	v_div_fixup_f32 v252, v238, v232, 1.0
	v_add_f32_e32 v233, 0, v158
	v_add_f32_e32 v233, v233, v159
	v_add_f32_e32 v233, v233, v160
	v_add_f32_e32 v233, v233, v161
	v_add_f32_e32 v233, v233, v162
	v_add_f32_e32 v233, v233, v163
	v_add_f32_e32 v233, v233, v164
	v_add_f32_e32 v233, v233, v165
	v_fmamk_f32 v233, v233, 0x3b000000, v221
	v_cmp_gt_f32_e32 vcc, s83, v233
	v_mul_f32_e32 v238, 0x4f800000, v233
	s_nop 0
	v_cndmask_b32_e32 v233, v233, v238, vcc
	v_sqrt_f32_e32 v238, v233
	s_nop 0
	v_add_u32_e32 v239, -1, v238
	v_fma_f32 v240, -v239, v238, v233
	v_cmp_ge_f32_e64 s[4:5], 0, v240
	v_add_u32_e32 v240, 1, v238
	s_nop 0
	v_cndmask_b32_e64 v239, v238, v239, s[4:5]
	v_fma_f32 v238, -v240, v238, v233
	v_cmp_lt_f32_e64 s[4:5], 0, v238
	s_nop 1
	v_cndmask_b32_e64 v238, v239, v240, s[4:5]
	v_mul_f32_e32 v239, 0x37800000, v238
	v_cndmask_b32_e32 v238, v238, v239, vcc
	v_cmp_class_f32_e32 vcc, v233, v222
	s_nop 1
	v_cndmask_b32_e32 v233, v238, v233, vcc
	v_div_scale_f32 v238, s[4:5], v233, v233, 1.0
	v_rcp_f32_e32 v239, v238
	s_nop 0
	v_fma_f32 v240, -v238, v239, 1.0
	v_fmac_f32_e32 v239, v240, v239
	v_div_scale_f32 v240, vcc, 1.0, v233, 1.0
	v_mul_f32_e32 v241, v240, v239
	v_fma_f32 v242, -v238, v241, v240
	v_fmac_f32_e32 v241, v242, v239
	v_fma_f32 v238, -v238, v241, v240
	s_nop 1
	v_div_fmas_f32 v238, v238, v239, v241
	v_div_fixup_f32 v253, v238, v233, 1.0
	s_waitcnt vmcnt(0)
	v_lshlrev_b32_e32 v238, 16, v102
	v_and_b32_e32 v239, 0xffff0000, v102
	v_lshlrev_b32_e32 v240, 16, v103
	v_and_b32_e32 v241, 0xffff0000, v103
	v_mul_f32_e32 v242, 0xbfb8aa3b, v238
	v_mul_f32_e32 v243, 0xbfb8aa3b, v239
	v_mul_f32_e32 v244, 0xbfb8aa3b, v240
	v_mul_f32_e32 v245, 0xbfb8aa3b, v241
	v_exp_f32_e32 v242, v242
	v_exp_f32_e32 v243, v243
	v_exp_f32_e32 v244, v244
	v_exp_f32_e32 v245, v245
	s_nop 0
	v_add_f32_e32 v242, 1.0, v242
	v_add_f32_e32 v243, 1.0, v243
	v_add_f32_e32 v244, 1.0, v244
	v_add_f32_e32 v245, 1.0, v245
	v_rcp_f32_e32 v242, v242
	v_rcp_f32_e32 v243, v243
	v_rcp_f32_e32 v244, v244
	v_rcp_f32_e32 v245, v245
	s_nop 0
	v_mul_f32_e32 v242, v242, v238
	v_mul_f32_e32 v243, v243, v239
	v_mul_f32_e32 v244, v244, v240
	v_mul_f32_e32 v245, v245, v241
	v_mul_f32_e32 v238, v0, v250
	v_mul_f32_e32 v239, v1, v250
	v_mul_f32_e32 v240, v2, v250
	v_mul_f32_e32 v241, v3, v250
	v_mul_f32_e32 v238, v238, v242
	v_mul_f32_e32 v239, v239, v243
	v_mul_f32_e32 v240, v240, v244
	v_mul_f32_e32 v241, v241, v245
	v_cvt_pk_bf16_f32 v102, v238, v239
	v_cvt_pk_bf16_f32 v103, v240, v241
	global_store_dwordx2 v226, v[102:103], s[86:87] offset:0
	v_lshlrev_b32_e32 v238, 16, v104
	v_and_b32_e32 v239, 0xffff0000, v104
	v_lshlrev_b32_e32 v240, 16, v105
	v_and_b32_e32 v241, 0xffff0000, v105
	v_mul_f32_e32 v242, 0xbfb8aa3b, v238
	v_mul_f32_e32 v243, 0xbfb8aa3b, v239
	v_mul_f32_e32 v244, 0xbfb8aa3b, v240
	v_mul_f32_e32 v245, 0xbfb8aa3b, v241
	v_exp_f32_e32 v242, v242
	v_exp_f32_e32 v243, v243
	v_exp_f32_e32 v244, v244
	v_exp_f32_e32 v245, v245
	s_nop 0
	v_add_f32_e32 v242, 1.0, v242
	v_add_f32_e32 v243, 1.0, v243
	v_add_f32_e32 v244, 1.0, v244
	v_add_f32_e32 v245, 1.0, v245
	v_rcp_f32_e32 v242, v242
	v_rcp_f32_e32 v243, v243
	v_rcp_f32_e32 v244, v244
	v_rcp_f32_e32 v245, v245
	s_nop 0
	v_mul_f32_e32 v242, v242, v238
	v_mul_f32_e32 v243, v243, v239
	v_mul_f32_e32 v244, v244, v240
	v_mul_f32_e32 v245, v245, v241
	v_mul_f32_e32 v238, v16, v250
	v_mul_f32_e32 v239, v17, v250
	v_mul_f32_e32 v240, v18, v250
	v_mul_f32_e32 v241, v19, v250
	v_mul_f32_e32 v238, v238, v242
	v_mul_f32_e32 v239, v239, v243
	v_mul_f32_e32 v240, v240, v244
	v_mul_f32_e32 v241, v241, v245
	v_cvt_pk_bf16_f32 v104, v238, v239
	v_cvt_pk_bf16_f32 v105, v240, v241
; __device__ __forceinline__ unsigned cvt_pk_bf16(float lo, float hi) { unsigned r; asm volatile("v_cvt_pk_bf16_f32 %0, %1, %2" : "=v"(r) : "v"(lo), "v"(hi)); return r; }
; __device__ __forceinline__ float bflo(unsigned w) { return __uint_as_float(w << 16); }
; __device__ __forceinline__ float bfhi(unsigned w) { return __uint_as_float(w & 0xffff0000u); }
; __device__ __forceinline__ float silu_f(float x) { return x * __builtin_amdgcn_rcpf(1.0f + __builtin_amdgcn_exp2f(x * -1.4426950408889634f)); }
; __device__ __forceinline__ void ret_unit(ldsp lds, bf16_t* R, const bf16_t* RC, int b, int h, int qblk, float lgf2, float lgb2, const int tid_in) {
;     ...
;         bf16_t* gp = R + (size_t)(rowq0 + 16 * q4 + l15) * 6144 + 4096 + h * 512 + 64 * wid + 4 * lg;
; #pragma unroll
;         for (int db = 0; db < 4; ++db) { const u32x2 g2 = *(const u32x2*)(gp + 16 * db);
;             u32x2 w; w.x = cvt_pk_bf16(o[db][q4][0] * rstd * silu_f(bflo(g2.x)), o[db][q4][1] * rstd * silu_f(bfhi(g2.x)));
;             w.y = cvt_pk_bf16(o[db][q4][2] * rstd * silu_f(bflo(g2.y)), o[db][q4][3] * rstd * silu_f(bfhi(g2.y)));
;             *(u32x2*)(gp + 16 * db) = w; }
;     }
	global_store_dwordx2 v226, v[104:105], s[86:87] offset:32
	v_lshlrev_b32_e32 v238, 16, v106
	v_and_b32_e32 v239, 0xffff0000, v106
	v_lshlrev_b32_e32 v240, 16, v107
	v_and_b32_e32 v241, 0xffff0000, v107
	v_mul_f32_e32 v242, 0xbfb8aa3b, v238
	v_mul_f32_e32 v243, 0xbfb8aa3b, v239
	v_mul_f32_e32 v244, 0xbfb8aa3b, v240
	v_mul_f32_e32 v245, 0xbfb8aa3b, v241
	v_exp_f32_e32 v242, v242
	v_exp_f32_e32 v243, v243
	v_exp_f32_e32 v244, v244
	v_exp_f32_e32 v245, v245
	s_nop 0
	v_add_f32_e32 v242, 1.0, v242
	v_add_f32_e32 v243, 1.0, v243
	v_add_f32_e32 v244, 1.0, v244
	v_add_f32_e32 v245, 1.0, v245
	v_rcp_f32_e32 v242, v242
	v_rcp_f32_e32 v243, v243
	v_rcp_f32_e32 v244, v244
	v_rcp_f32_e32 v245, v245
	s_nop 0
	v_mul_f32_e32 v242, v242, v238
	v_mul_f32_e32 v243, v243, v239
	v_mul_f32_e32 v244, v244, v240
	v_mul_f32_e32 v245, v245, v241
	v_mul_f32_e32 v238, v32, v250
	v_mul_f32_e32 v239, v33, v250
	v_mul_f32_e32 v240, v34, v250
	v_mul_f32_e32 v241, v35, v250
	v_mul_f32_e32 v238, v238, v242
	v_mul_f32_e32 v239, v239, v243
	v_mul_f32_e32 v240, v240, v244
	v_mul_f32_e32 v241, v241, v245
	v_cvt_pk_bf16_f32 v106, v238, v239
	v_cvt_pk_bf16_f32 v107, v240, v241
	global_store_dwordx2 v226, v[106:107], s[86:87] offset:64
	v_lshlrev_b32_e32 v238, 16, v108
	v_and_b32_e32 v239, 0xffff0000, v108
	v_lshlrev_b32_e32 v240, 16, v109
	v_and_b32_e32 v241, 0xffff0000, v109
	v_mul_f32_e32 v242, 0xbfb8aa3b, v238
	v_mul_f32_e32 v243, 0xbfb8aa3b, v239
	v_mul_f32_e32 v244, 0xbfb8aa3b, v240
	v_mul_f32_e32 v245, 0xbfb8aa3b, v241
	v_exp_f32_e32 v242, v242
	v_exp_f32_e32 v243, v243
	v_exp_f32_e32 v244, v244
	v_exp_f32_e32 v245, v245
	s_nop 0
	v_add_f32_e32 v242, 1.0, v242
	v_add_f32_e32 v243, 1.0, v243
	v_add_f32_e32 v244, 1.0, v244
	v_add_f32_e32 v245, 1.0, v245
	v_rcp_f32_e32 v242, v242
	v_rcp_f32_e32 v243, v243
	v_rcp_f32_e32 v244, v244
	v_rcp_f32_e32 v245, v245
	s_nop 0
	v_mul_f32_e32 v242, v242, v238
	v_mul_f32_e32 v243, v243, v239
	v_mul_f32_e32 v244, v244, v240
	v_mul_f32_e32 v245, v245, v241
	v_mul_f32_e32 v238, v48, v250
	v_mul_f32_e32 v239, v49, v250
	v_mul_f32_e32 v240, v50, v250
	v_mul_f32_e32 v241, v51, v250
	v_mul_f32_e32 v238, v238, v242
	v_mul_f32_e32 v239, v239, v243
	v_mul_f32_e32 v240, v240, v244
	v_mul_f32_e32 v241, v241, v245
	v_cvt_pk_bf16_f32 v108, v238, v239
	v_cvt_pk_bf16_f32 v109, v240, v241
	global_store_dwordx2 v226, v[108:109], s[86:87] offset:96
	v_lshlrev_b32_e32 v238, 16, v110
	v_and_b32_e32 v239, 0xffff0000, v110
	v_lshlrev_b32_e32 v240, 16, v111
	v_and_b32_e32 v241, 0xffff0000, v111
	v_mul_f32_e32 v242, 0xbfb8aa3b, v238
	v_mul_f32_e32 v243, 0xbfb8aa3b, v239
	v_mul_f32_e32 v244, 0xbfb8aa3b, v240
	v_mul_f32_e32 v245, 0xbfb8aa3b, v241
	v_exp_f32_e32 v242, v242
	v_exp_f32_e32 v243, v243
	v_exp_f32_e32 v244, v244
	v_exp_f32_e32 v245, v245
	s_nop 0
	v_add_f32_e32 v242, 1.0, v242
	v_add_f32_e32 v243, 1.0, v243
	v_add_f32_e32 v244, 1.0, v244
	v_add_f32_e32 v245, 1.0, v245
	v_rcp_f32_e32 v242, v242
	v_rcp_f32_e32 v243, v243
	v_rcp_f32_e32 v244, v244
	v_rcp_f32_e32 v245, v245
	s_nop 0
	v_mul_f32_e32 v242, v242, v238
	v_mul_f32_e32 v243, v243, v239
	v_mul_f32_e32 v244, v244, v240
	v_mul_f32_e32 v245, v245, v241
	v_mul_f32_e32 v238, v4, v251
	v_mul_f32_e32 v239, v5, v251
	v_mul_f32_e32 v240, v6, v251
	v_mul_f32_e32 v241, v7, v251
	v_mul_f32_e32 v238, v238, v242
	v_mul_f32_e32 v239, v239, v243
	v_mul_f32_e32 v240, v240, v244
	v_mul_f32_e32 v241, v241, v245
	v_cvt_pk_bf16_f32 v110, v238, v239
	v_cvt_pk_bf16_f32 v111, v240, v241
	global_store_dwordx2 v227, v[110:111], s[86:87] offset:0
	v_lshlrev_b32_e32 v238, 16, v112
	v_and_b32_e32 v239, 0xffff0000, v112
	v_lshlrev_b32_e32 v240, 16, v113
	v_and_b32_e32 v241, 0xffff0000, v113
	v_mul_f32_e32 v242, 0xbfb8aa3b, v238
	v_mul_f32_e32 v243, 0xbfb8aa3b, v239
	v_mul_f32_e32 v244, 0xbfb8aa3b, v240
	v_mul_f32_e32 v245, 0xbfb8aa3b, v241
	v_exp_f32_e32 v242, v242
	v_exp_f32_e32 v243, v243
	v_exp_f32_e32 v244, v244
	v_exp_f32_e32 v245, v245
	s_nop 0
	v_add_f32_e32 v242, 1.0, v242
	v_add_f32_e32 v243, 1.0, v243
	v_add_f32_e32 v244, 1.0, v244
	v_add_f32_e32 v245, 1.0, v245
	v_rcp_f32_e32 v242, v242
	v_rcp_f32_e32 v243, v243
	v_rcp_f32_e32 v244, v244
	v_rcp_f32_e32 v245, v245
	s_nop 0
	v_mul_f32_e32 v242, v242, v238
	v_mul_f32_e32 v243, v243, v239
	v_mul_f32_e32 v244, v244, v240
	v_mul_f32_e32 v245, v245, v241
	v_mul_f32_e32 v238, v20, v251
	v_mul_f32_e32 v239, v21, v251
	v_mul_f32_e32 v240, v22, v251
	v_mul_f32_e32 v241, v23, v251
	v_mul_f32_e32 v238, v238, v242
	v_mul_f32_e32 v239, v239, v243
	v_mul_f32_e32 v240, v240, v244
	v_mul_f32_e32 v241, v241, v245
	v_cvt_pk_bf16_f32 v112, v238, v239
	v_cvt_pk_bf16_f32 v113, v240, v241
	global_store_dwordx2 v227, v[112:113], s[86:87] offset:32
	v_lshlrev_b32_e32 v238, 16, v114
	v_and_b32_e32 v239, 0xffff0000, v114
	v_lshlrev_b32_e32 v240, 16, v115
	v_and_b32_e32 v241, 0xffff0000, v115
	v_mul_f32_e32 v242, 0xbfb8aa3b, v238
	v_mul_f32_e32 v243, 0xbfb8aa3b, v239
	v_mul_f32_e32 v244, 0xbfb8aa3b, v240
	v_mul_f32_e32 v245, 0xbfb8aa3b, v241
	v_exp_f32_e32 v242, v242
	v_exp_f32_e32 v243, v243
	v_exp_f32_e32 v244, v244
	v_exp_f32_e32 v245, v245
	s_nop 0
	v_add_f32_e32 v242, 1.0, v242
	v_add_f32_e32 v243, 1.0, v243
	v_add_f32_e32 v244, 1.0, v244
	v_add_f32_e32 v245, 1.0, v245
	v_rcp_f32_e32 v242, v242
	v_rcp_f32_e32 v243, v243
	v_rcp_f32_e32 v244, v244
	v_rcp_f32_e32 v245, v245
	s_nop 0
	v_mul_f32_e32 v242, v242, v238
	v_mul_f32_e32 v243, v243, v239
	v_mul_f32_e32 v244, v244, v240
	v_mul_f32_e32 v245, v245, v241
	v_mul_f32_e32 v238, v36, v251
	v_mul_f32_e32 v239, v37, v251
	v_mul_f32_e32 v240, v38, v251
	v_mul_f32_e32 v241, v39, v251
	v_mul_f32_e32 v238, v238, v242
	v_mul_f32_e32 v239, v239, v243
; __device__ __forceinline__ unsigned cvt_pk_bf16(float lo, float hi) { unsigned r; asm volatile("v_cvt_pk_bf16_f32 %0, %1, %2" : "=v"(r) : "v"(lo), "v"(hi)); return r; }
; __device__ __forceinline__ float bflo(unsigned w) { return __uint_as_float(w << 16); }
; __device__ __forceinline__ float bfhi(unsigned w) { return __uint_as_float(w & 0xffff0000u); }
; __device__ __forceinline__ float silu_f(float x) { return x * __builtin_amdgcn_rcpf(1.0f + __builtin_amdgcn_exp2f(x * -1.4426950408889634f)); }
; __device__ __forceinline__ void ret_unit(ldsp lds, bf16_t* R, const bf16_t* RC, int b, int h, int qblk, float lgf2, float lgb2, const int tid_in) {
;     ...
;         bf16_t* gp = R + (size_t)(rowq0 + 16 * q4 + l15) * 6144 + 4096 + h * 512 + 64 * wid + 4 * lg;
; #pragma unroll
;         for (int db = 0; db < 4; ++db) { const u32x2 g2 = *(const u32x2*)(gp + 16 * db);
;             u32x2 w; w.x = cvt_pk_bf16(o[db][q4][0] * rstd * silu_f(bflo(g2.x)), o[db][q4][1] * rstd * silu_f(bfhi(g2.x)));
;             w.y = cvt_pk_bf16(o[db][q4][2] * rstd * silu_f(bflo(g2.y)), o[db][q4][3] * rstd * silu_f(bfhi(g2.y)));
;             *(u32x2*)(gp + 16 * db) = w; }
;     }
	v_mul_f32_e32 v240, v240, v244
	v_mul_f32_e32 v241, v241, v245
	v_cvt_pk_bf16_f32 v114, v238, v239
	v_cvt_pk_bf16_f32 v115, v240, v241
	global_store_dwordx2 v227, v[114:115], s[86:87] offset:64
	v_lshlrev_b32_e32 v238, 16, v116
	v_and_b32_e32 v239, 0xffff0000, v116
	v_lshlrev_b32_e32 v240, 16, v117
	v_and_b32_e32 v241, 0xffff0000, v117
	v_mul_f32_e32 v242, 0xbfb8aa3b, v238
	v_mul_f32_e32 v243, 0xbfb8aa3b, v239
	v_mul_f32_e32 v244, 0xbfb8aa3b, v240
	v_mul_f32_e32 v245, 0xbfb8aa3b, v241
	v_exp_f32_e32 v242, v242
	v_exp_f32_e32 v243, v243
	v_exp_f32_e32 v244, v244
	v_exp_f32_e32 v245, v245
	s_nop 0
	v_add_f32_e32 v242, 1.0, v242
	v_add_f32_e32 v243, 1.0, v243
	v_add_f32_e32 v244, 1.0, v244
	v_add_f32_e32 v245, 1.0, v245
	v_rcp_f32_e32 v242, v242
	v_rcp_f32_e32 v243, v243
	v_rcp_f32_e32 v244, v244
	v_rcp_f32_e32 v245, v245
	s_nop 0
	v_mul_f32_e32 v242, v242, v238
	v_mul_f32_e32 v243, v243, v239
	v_mul_f32_e32 v244, v244, v240
	v_mul_f32_e32 v245, v245, v241
	v_mul_f32_e32 v238, v52, v251
	v_mul_f32_e32 v239, v53, v251
	v_mul_f32_e32 v240, v54, v251
	v_mul_f32_e32 v241, v55, v251
	v_mul_f32_e32 v238, v238, v242
	v_mul_f32_e32 v239, v239, v243
	v_mul_f32_e32 v240, v240, v244
	v_mul_f32_e32 v241, v241, v245
	v_cvt_pk_bf16_f32 v116, v238, v239
	v_cvt_pk_bf16_f32 v117, v240, v241
	global_store_dwordx2 v227, v[116:117], s[86:87] offset:96
	v_lshlrev_b32_e32 v238, 16, v118
	v_and_b32_e32 v239, 0xffff0000, v118
	v_lshlrev_b32_e32 v240, 16, v119
	v_and_b32_e32 v241, 0xffff0000, v119
	v_mul_f32_e32 v242, 0xbfb8aa3b, v238
	v_mul_f32_e32 v243, 0xbfb8aa3b, v239
	v_mul_f32_e32 v244, 0xbfb8aa3b, v240
	v_mul_f32_e32 v245, 0xbfb8aa3b, v241
	v_exp_f32_e32 v242, v242
	v_exp_f32_e32 v243, v243
	v_exp_f32_e32 v244, v244
	v_exp_f32_e32 v245, v245
	s_nop 0
	v_add_f32_e32 v242, 1.0, v242
	v_add_f32_e32 v243, 1.0, v243
	v_add_f32_e32 v244, 1.0, v244
	v_add_f32_e32 v245, 1.0, v245
	v_rcp_f32_e32 v242, v242
	v_rcp_f32_e32 v243, v243
	v_rcp_f32_e32 v244, v244
	v_rcp_f32_e32 v245, v245
	s_nop 0
	v_mul_f32_e32 v242, v242, v238
	v_mul_f32_e32 v243, v243, v239
	v_mul_f32_e32 v244, v244, v240
	v_mul_f32_e32 v245, v245, v241
	v_mul_f32_e32 v238, v8, v252
	v_mul_f32_e32 v239, v9, v252
	v_mul_f32_e32 v240, v10, v252
	v_mul_f32_e32 v241, v11, v252
	v_mul_f32_e32 v238, v238, v242
	v_mul_f32_e32 v239, v239, v243
	v_mul_f32_e32 v240, v240, v244
	v_mul_f32_e32 v241, v241, v245
	v_cvt_pk_bf16_f32 v118, v238, v239
	v_cvt_pk_bf16_f32 v119, v240, v241
	global_store_dwordx2 v228, v[118:119], s[86:87] offset:0
	v_lshlrev_b32_e32 v238, 16, v120
	v_and_b32_e32 v239, 0xffff0000, v120
	v_lshlrev_b32_e32 v240, 16, v121
	v_and_b32_e32 v241, 0xffff0000, v121
	v_mul_f32_e32 v242, 0xbfb8aa3b, v238
	v_mul_f32_e32 v243, 0xbfb8aa3b, v239
	v_mul_f32_e32 v244, 0xbfb8aa3b, v240
	v_mul_f32_e32 v245, 0xbfb8aa3b, v241
	v_exp_f32_e32 v242, v242
	v_exp_f32_e32 v243, v243
	v_exp_f32_e32 v244, v244
	v_exp_f32_e32 v245, v245
	s_nop 0
	v_add_f32_e32 v242, 1.0, v242
	v_add_f32_e32 v243, 1.0, v243
	v_add_f32_e32 v244, 1.0, v244
	v_add_f32_e32 v245, 1.0, v245
	v_rcp_f32_e32 v242, v242
	v_rcp_f32_e32 v243, v243
	v_rcp_f32_e32 v244, v244
	v_rcp_f32_e32 v245, v245
	s_nop 0
	v_mul_f32_e32 v242, v242, v238
	v_mul_f32_e32 v243, v243, v239
	v_mul_f32_e32 v244, v244, v240
	v_mul_f32_e32 v245, v245, v241
	v_mul_f32_e32 v238, v24, v252
	v_mul_f32_e32 v239, v25, v252
	v_mul_f32_e32 v240, v26, v252
	v_mul_f32_e32 v241, v27, v252
	v_mul_f32_e32 v238, v238, v242
	v_mul_f32_e32 v239, v239, v243
	v_mul_f32_e32 v240, v240, v244
	v_mul_f32_e32 v241, v241, v245
	v_cvt_pk_bf16_f32 v120, v238, v239
	v_cvt_pk_bf16_f32 v121, v240, v241
	global_store_dwordx2 v228, v[120:121], s[86:87] offset:32
	v_lshlrev_b32_e32 v238, 16, v122
	v_and_b32_e32 v239, 0xffff0000, v122
	v_lshlrev_b32_e32 v240, 16, v123
	v_and_b32_e32 v241, 0xffff0000, v123
	v_mul_f32_e32 v242, 0xbfb8aa3b, v238
	v_mul_f32_e32 v243, 0xbfb8aa3b, v239
	v_mul_f32_e32 v244, 0xbfb8aa3b, v240
	v_mul_f32_e32 v245, 0xbfb8aa3b, v241
	v_exp_f32_e32 v242, v242
	v_exp_f32_e32 v243, v243
	v_exp_f32_e32 v244, v244
	v_exp_f32_e32 v245, v245
	s_nop 0
	v_add_f32_e32 v242, 1.0, v242
	v_add_f32_e32 v243, 1.0, v243
	v_add_f32_e32 v244, 1.0, v244
	v_add_f32_e32 v245, 1.0, v245
	v_rcp_f32_e32 v242, v242
	v_rcp_f32_e32 v243, v243
	v_rcp_f32_e32 v244, v244
	v_rcp_f32_e32 v245, v245
	s_nop 0
	v_mul_f32_e32 v242, v242, v238
	v_mul_f32_e32 v243, v243, v239
	v_mul_f32_e32 v244, v244, v240
	v_mul_f32_e32 v245, v245, v241
	v_mul_f32_e32 v238, v40, v252
	v_mul_f32_e32 v239, v41, v252
	v_mul_f32_e32 v240, v42, v252
	v_mul_f32_e32 v241, v43, v252
	v_mul_f32_e32 v238, v238, v242
	v_mul_f32_e32 v239, v239, v243
	v_mul_f32_e32 v240, v240, v244
	v_mul_f32_e32 v241, v241, v245
	v_cvt_pk_bf16_f32 v122, v238, v239
	v_cvt_pk_bf16_f32 v123, v240, v241
	global_store_dwordx2 v228, v[122:123], s[86:87] offset:64
	v_lshlrev_b32_e32 v238, 16, v124
	v_and_b32_e32 v239, 0xffff0000, v124
	v_lshlrev_b32_e32 v240, 16, v125
	v_and_b32_e32 v241, 0xffff0000, v125
	v_mul_f32_e32 v242, 0xbfb8aa3b, v238
	v_mul_f32_e32 v243, 0xbfb8aa3b, v239
	v_mul_f32_e32 v244, 0xbfb8aa3b, v240
	v_mul_f32_e32 v245, 0xbfb8aa3b, v241
	v_exp_f32_e32 v242, v242
	v_exp_f32_e32 v243, v243
	v_exp_f32_e32 v244, v244
	v_exp_f32_e32 v245, v245
	s_nop 0
	v_add_f32_e32 v242, 1.0, v242
	v_add_f32_e32 v243, 1.0, v243
	v_add_f32_e32 v244, 1.0, v244
; __device__ __forceinline__ unsigned cvt_pk_bf16(float lo, float hi) { unsigned r; asm volatile("v_cvt_pk_bf16_f32 %0, %1, %2" : "=v"(r) : "v"(lo), "v"(hi)); return r; }
; __device__ __forceinline__ float bflo(unsigned w) { return __uint_as_float(w << 16); }
; __device__ __forceinline__ float bfhi(unsigned w) { return __uint_as_float(w & 0xffff0000u); }
; __device__ __forceinline__ float silu_f(float x) { return x * __builtin_amdgcn_rcpf(1.0f + __builtin_amdgcn_exp2f(x * -1.4426950408889634f)); }
; #define RET_BAR() do { asm volatile("s_waitcnt lgkmcnt(0)" ::: "memory"); __builtin_amdgcn_s_barrier(); asm volatile("" ::: "memory"); } while (0)
; __device__ __forceinline__ void ret_unit(ldsp lds, bf16_t* R, const bf16_t* RC, int b, int h, int qblk, float lgf2, float lgb2, const int tid_in) {
;     ...
;         bf16_t* gp = R + (size_t)(rowq0 + 16 * q4 + l15) * 6144 + 4096 + h * 512 + 64 * wid + 4 * lg;
; #pragma unroll
;         for (int db = 0; db < 4; ++db) { const u32x2 g2 = *(const u32x2*)(gp + 16 * db);
;             u32x2 w; w.x = cvt_pk_bf16(o[db][q4][0] * rstd * silu_f(bflo(g2.x)), o[db][q4][1] * rstd * silu_f(bfhi(g2.x)));
;             w.y = cvt_pk_bf16(o[db][q4][2] * rstd * silu_f(bflo(g2.y)), o[db][q4][3] * rstd * silu_f(bfhi(g2.y)));
;             *(u32x2*)(gp + 16 * db) = w; }
;     }
;     RET_BAR();
;     ...
; }
; __device__ __forceinline__ void ret_phase(ldsp lds, bf16_t* R, const bf16_t* RC, const float* decay, const int tid, const int bx) {
;     const int xcd = bx & 7, slot = bx >> 3;
;     for (int i = 0; i < 4; ++i) {
;         const int bh = 8 * i + xcd, b = bh >> 2, h = bh & 3;
;         const float lgf2 = decay[h], lgb2 = decay[4 + h];
;         ret_unit(lds, R, RC, b, h, slot, lgf2, lgb2, tid);
;     }
; }
	v_add_f32_e32 v245, 1.0, v245
	v_rcp_f32_e32 v242, v242
	v_rcp_f32_e32 v243, v243
	v_rcp_f32_e32 v244, v244
	v_rcp_f32_e32 v245, v245
	s_nop 0
	v_mul_f32_e32 v242, v242, v238
	v_mul_f32_e32 v243, v243, v239
	v_mul_f32_e32 v244, v244, v240
	v_mul_f32_e32 v245, v245, v241
	v_mul_f32_e32 v238, v56, v252
	v_mul_f32_e32 v239, v57, v252
	v_mul_f32_e32 v240, v58, v252
	v_mul_f32_e32 v241, v59, v252
	v_mul_f32_e32 v238, v238, v242
	v_mul_f32_e32 v239, v239, v243
	v_mul_f32_e32 v240, v240, v244
	v_mul_f32_e32 v241, v241, v245
	v_cvt_pk_bf16_f32 v124, v238, v239
	v_cvt_pk_bf16_f32 v125, v240, v241
	global_store_dwordx2 v228, v[124:125], s[86:87] offset:96
	v_lshlrev_b32_e32 v238, 16, v126
	v_and_b32_e32 v239, 0xffff0000, v126
	v_lshlrev_b32_e32 v240, 16, v127
	v_and_b32_e32 v241, 0xffff0000, v127
	v_mul_f32_e32 v242, 0xbfb8aa3b, v238
	v_mul_f32_e32 v243, 0xbfb8aa3b, v239
	v_mul_f32_e32 v244, 0xbfb8aa3b, v240
	v_mul_f32_e32 v245, 0xbfb8aa3b, v241
	v_exp_f32_e32 v242, v242
	v_exp_f32_e32 v243, v243
	v_exp_f32_e32 v244, v244
	v_exp_f32_e32 v245, v245
	s_nop 0
	v_add_f32_e32 v242, 1.0, v242
	v_add_f32_e32 v243, 1.0, v243
	v_add_f32_e32 v244, 1.0, v244
	v_add_f32_e32 v245, 1.0, v245
	v_rcp_f32_e32 v242, v242
	v_rcp_f32_e32 v243, v243
	v_rcp_f32_e32 v244, v244
	v_rcp_f32_e32 v245, v245
	s_nop 0
	v_mul_f32_e32 v242, v242, v238
	v_mul_f32_e32 v243, v243, v239
	v_mul_f32_e32 v244, v244, v240
	v_mul_f32_e32 v245, v245, v241
	v_mul_f32_e32 v238, v12, v253
	v_mul_f32_e32 v239, v13, v253
	v_mul_f32_e32 v240, v14, v253
	v_mul_f32_e32 v241, v15, v253
	v_mul_f32_e32 v238, v238, v242
	v_mul_f32_e32 v239, v239, v243
	v_mul_f32_e32 v240, v240, v244
	v_mul_f32_e32 v241, v241, v245
	v_cvt_pk_bf16_f32 v126, v238, v239
	v_cvt_pk_bf16_f32 v127, v240, v241
	global_store_dwordx2 v229, v[126:127], s[86:87] offset:0
	v_lshlrev_b32_e32 v238, 16, v128
	v_and_b32_e32 v239, 0xffff0000, v128
	v_lshlrev_b32_e32 v240, 16, v129
	v_and_b32_e32 v241, 0xffff0000, v129
	v_mul_f32_e32 v242, 0xbfb8aa3b, v238
	v_mul_f32_e32 v243, 0xbfb8aa3b, v239
	v_mul_f32_e32 v244, 0xbfb8aa3b, v240
	v_mul_f32_e32 v245, 0xbfb8aa3b, v241
	v_exp_f32_e32 v242, v242
	v_exp_f32_e32 v243, v243
	v_exp_f32_e32 v244, v244
	v_exp_f32_e32 v245, v245
	s_nop 0
	v_add_f32_e32 v242, 1.0, v242
	v_add_f32_e32 v243, 1.0, v243
	v_add_f32_e32 v244, 1.0, v244
	v_add_f32_e32 v245, 1.0, v245
	v_rcp_f32_e32 v242, v242
	v_rcp_f32_e32 v243, v243
	v_rcp_f32_e32 v244, v244
	v_rcp_f32_e32 v245, v245
	s_nop 0
	v_mul_f32_e32 v242, v242, v238
	v_mul_f32_e32 v243, v243, v239
	v_mul_f32_e32 v244, v244, v240
	v_mul_f32_e32 v245, v245, v241
	v_mul_f32_e32 v238, v28, v253
	v_mul_f32_e32 v239, v29, v253
	v_mul_f32_e32 v240, v30, v253
	v_mul_f32_e32 v241, v31, v253
	v_mul_f32_e32 v238, v238, v242
	v_mul_f32_e32 v239, v239, v243
	v_mul_f32_e32 v240, v240, v244
	v_mul_f32_e32 v241, v241, v245
	v_cvt_pk_bf16_f32 v128, v238, v239
	v_cvt_pk_bf16_f32 v129, v240, v241
	global_store_dwordx2 v229, v[128:129], s[86:87] offset:32
	v_lshlrev_b32_e32 v238, 16, v130
	v_and_b32_e32 v239, 0xffff0000, v130
	v_lshlrev_b32_e32 v240, 16, v131
	v_and_b32_e32 v241, 0xffff0000, v131
	v_mul_f32_e32 v242, 0xbfb8aa3b, v238
	v_mul_f32_e32 v243, 0xbfb8aa3b, v239
	v_mul_f32_e32 v244, 0xbfb8aa3b, v240
	v_mul_f32_e32 v245, 0xbfb8aa3b, v241
	v_exp_f32_e32 v242, v242
	v_exp_f32_e32 v243, v243
	v_exp_f32_e32 v244, v244
	v_exp_f32_e32 v245, v245
	s_nop 0
	v_add_f32_e32 v242, 1.0, v242
	v_add_f32_e32 v243, 1.0, v243
	v_add_f32_e32 v244, 1.0, v244
	v_add_f32_e32 v245, 1.0, v245
	v_rcp_f32_e32 v242, v242
	v_rcp_f32_e32 v243, v243
	v_rcp_f32_e32 v244, v244
	v_rcp_f32_e32 v245, v245
	s_nop 0
	v_mul_f32_e32 v242, v242, v238
	v_mul_f32_e32 v243, v243, v239
	v_mul_f32_e32 v244, v244, v240
	v_mul_f32_e32 v245, v245, v241
	v_mul_f32_e32 v238, v44, v253
	v_mul_f32_e32 v239, v45, v253
	v_mul_f32_e32 v240, v46, v253
	v_mul_f32_e32 v241, v47, v253
	v_mul_f32_e32 v238, v238, v242
	v_mul_f32_e32 v239, v239, v243
	v_mul_f32_e32 v240, v240, v244
	v_mul_f32_e32 v241, v241, v245
	v_cvt_pk_bf16_f32 v130, v238, v239
	v_cvt_pk_bf16_f32 v131, v240, v241
	global_store_dwordx2 v229, v[130:131], s[86:87] offset:64
	v_lshlrev_b32_e32 v238, 16, v132
	v_and_b32_e32 v239, 0xffff0000, v132
	v_lshlrev_b32_e32 v240, 16, v133
	v_and_b32_e32 v241, 0xffff0000, v133
	v_mul_f32_e32 v242, 0xbfb8aa3b, v238
	v_mul_f32_e32 v243, 0xbfb8aa3b, v239
	v_mul_f32_e32 v244, 0xbfb8aa3b, v240
	v_mul_f32_e32 v245, 0xbfb8aa3b, v241
	v_exp_f32_e32 v242, v242
	v_exp_f32_e32 v243, v243
	v_exp_f32_e32 v244, v244
	v_exp_f32_e32 v245, v245
	s_nop 0
	v_add_f32_e32 v242, 1.0, v242
	v_add_f32_e32 v243, 1.0, v243
	v_add_f32_e32 v244, 1.0, v244
	v_add_f32_e32 v245, 1.0, v245
	v_rcp_f32_e32 v242, v242
	v_rcp_f32_e32 v243, v243
	v_rcp_f32_e32 v244, v244
	v_rcp_f32_e32 v245, v245
	s_nop 0
	v_mul_f32_e32 v242, v242, v238
	v_mul_f32_e32 v243, v243, v239
	v_mul_f32_e32 v244, v244, v240
	v_mul_f32_e32 v245, v245, v241
	v_mul_f32_e32 v238, v60, v253
	v_mul_f32_e32 v239, v61, v253
	v_mul_f32_e32 v240, v62, v253
	v_mul_f32_e32 v241, v63, v253
	v_mul_f32_e32 v238, v238, v242
	v_mul_f32_e32 v239, v239, v243
	v_mul_f32_e32 v240, v240, v244
	v_mul_f32_e32 v241, v241, v245
	v_cvt_pk_bf16_f32 v132, v238, v239
	v_cvt_pk_bf16_f32 v133, v240, v241
	global_store_dwordx2 v229, v[132:133], s[86:87] offset:96
	s_add_i32 s3, s3, 1
	s_cmp_lt_u32 s3, 4
	s_cbranch_scc1 .Lret_unit

; __global__ void __launch_bounds__(512, 2) fwd_megakernel(Args a_in) {
	.amdhsa_kernel _Z14fwd_megakernel4Args
		.amdhsa_group_segment_fixed_size 0
		.amdhsa_private_segment_fixed_size 0
		.amdhsa_kernarg_size 472
		.amdhsa_user_sgpr_count 2
		.amdhsa_user_sgpr_dispatch_ptr 0
		.amdhsa_user_sgpr_queue_ptr 0
		.amdhsa_user_sgpr_kernarg_segment_ptr 1
		.amdhsa_user_sgpr_dispatch_id 0
		.amdhsa_user_sgpr_kernarg_preload_length 0
		.amdhsa_user_sgpr_kernarg_preload_offset 0
		.amdhsa_user_sgpr_private_segment_size 0
		.amdhsa_uses_dynamic_stack 0
		.amdhsa_enable_private_segment 0
		.amdhsa_system_sgpr_workgroup_id_x 1
		.amdhsa_system_sgpr_workgroup_id_y 0
		.amdhsa_system_sgpr_workgroup_id_z 0
		.amdhsa_system_sgpr_workgroup_info 0
		.amdhsa_system_vgpr_workitem_id 2
		.amdhsa_next_free_vgpr 256
		.amdhsa_next_free_sgpr 102
		.amdhsa_accum_offset 256
		.amdhsa_reserve_vcc 1
		.amdhsa_float_round_mode_32 0
		.amdhsa_float_round_mode_16_64 0
		.amdhsa_float_denorm_mode_32 3
		.amdhsa_float_denorm_mode_16_64 3
		.amdhsa_dx10_clamp 1
		.amdhsa_ieee_mode 1
		.amdhsa_fp16_overflow 0
		.amdhsa_tg_split 0
		.amdhsa_exception_fp_ieee_invalid_op 0
		.amdhsa_exception_fp_denorm_src 0
		.amdhsa_exception_fp_ieee_div_zero 0
		.amdhsa_exception_fp_ieee_overflow 0
		.amdhsa_exception_fp_ieee_underflow 0
		.amdhsa_exception_fp_ieee_inexact 0
		.amdhsa_exception_int_div_zero 0
	.end_amdhsa_kernel

; __global__ void __launch_bounds__(512, 2) fwd_megakernel(Args a_in) {
amdhsa.kernels:
  - .agpr_count:     0
    .args:
      - .offset:         0
        .size:           216
        .value_kind:     by_value
      - .offset:         216
        .size:           4
        .value_kind:     hidden_block_count_x
      - .offset:         220
        .size:           4
        .value_kind:     hidden_block_count_y
      - .offset:         224
        .size:           4
        .value_kind:     hidden_block_count_z
      - .offset:         228
        .size:           2
        .value_kind:     hidden_group_size_x
      - .offset:         230
        .size:           2
        .value_kind:     hidden_group_size_y
      - .offset:         232
        .size:           2
        .value_kind:     hidden_group_size_z
      - .offset:         234
        .size:           2
        .value_kind:     hidden_remainder_x
      - .offset:         236
        .size:           2
        .value_kind:     hidden_remainder_y
      - .offset:         238
        .size:           2
        .value_kind:     hidden_remainder_z
      - .offset:         256
        .size:           8
        .value_kind:     hidden_global_offset_x
      - .offset:         264
        .size:           8
        .value_kind:     hidden_global_offset_y
      - .offset:         272
        .size:           8
        .value_kind:     hidden_global_offset_z
      - .offset:         280
        .size:           2
        .value_kind:     hidden_grid_dims
      - .offset:         304
        .size:           8
        .value_kind:     hidden_multigrid_sync_arg
      - .offset:         336
        .size:           4
        .value_kind:     hidden_dynamic_lds_size
    .group_segment_fixed_size: 0
    .kernarg_segment_align: 8
    .kernarg_segment_size: 472
    .language:       OpenCL C
    .language_version:
      - 2
      - 0
    .max_flat_workgroup_size: 512
    .name:           _Z14fwd_megakernel4Args
    .private_segment_fixed_size: 0
    .sgpr_count:     108
    .sgpr_spill_count: 94
    .symbol:         _Z14fwd_megakernel4Args.kd
    .uniform_work_group_size: 1
    .uses_dynamic_stack: false
    .vgpr_count:     256
    .vgpr_spill_count: 0
    .wavefront_size: 64
